# workgroup barrier at every gather unit (U and V loops): the 8 waves stay in lockstep on the same table slice
# speedup vs baseline: 1.0276x; 1.0003x over previous
; #define PG_ISSUE(BUF, TAB, e0_) do { const int isrc_ = ((e0_) < 64) ? myi0 : myi1; \
;       _Pragma("unroll") for (int e = 0; e < 8; ++e) { const int idx_ = __builtin_amdgcn_readlane(isrc_, ((e0_) + e) & 63); \
;         BUF[e] = *(const u32x4*)((TAB) + (size_t)idx_ * 1024 + lane * 16); } } while (0)
; DEV void peer_gather(const Params& P, int l, int m0, const int* idxs, const float* gs) {
;     ...
;     PG_ISSUE(b0, U, 0);
; #pragma nounroll
;     for (int e0 = 0; e0 < 128; e0 += 16) {
;       PG_ISSUE(b1, U, e0 + 8);
;       PG_U8(b0, 0, e0);
;       if (e0 + 16 < 128) PG_ISSUE(b0, U, e0 + 16); else PG_ISSUE(b0, V, 0);
;       PG_U8(b1, 0, e0 + 8);
;     }
.Lpg0_uloop:
	s_barrier
	s_and_b32 s98, s100, 15
	s_add_u32 s92, s100, 1
	s_min_u32 s92, s92, 127
	s_lshr_b32 s93, s92, 4
	s_and_b32 s92, s92, 15
	s_waitcnt vmcnt(16) lgkmcnt(0)
	v_mov_b32_e32 v64, v80
	v_mov_b32_e32 v65, v81
	v_mov_b32_e32 v66, v82
	v_mov_b32_e32 v67, v83
	v_mov_b32_e32 v68, v84
	v_mov_b32_e32 v69, v85
	v_mov_b32_e32 v70, v86
	v_mov_b32_e32 v71, v87
	s_lshl3_add_u32 vcc_lo, s92, s93
	v_lshl_add_u32 v119, vcc_lo, 8, v236
	global_load_dwordx4 v[80:83], v119, s[82:83]
	global_load_dwordx4 v[84:87], v119, s[82:83] offset:16
	v_lshl_or_b32 v240, s93, 21, v235
	s_waitcnt vmcnt(16)
	v_cvt_scalef32_pk_bf16_fp8 v104, v0, 1.0
	v_cvt_scalef32_pk_bf16_fp8 v105, v0, 1.0 op_sel:[1,0,0]
	v_cvt_scalef32_pk_bf16_fp8 v106, v4, 1.0
	v_cvt_scalef32_pk_bf16_fp8 v107, v4, 1.0 op_sel:[1,0,0]
	v_cvt_scalef32_pk_bf16_fp8 v108, v1, 1.0
	v_cvt_scalef32_pk_bf16_fp8 v109, v1, 1.0 op_sel:[1,0,0]
	v_mfma_f32_4x4x4_16b_bf16 v[72:75], v[104:105], v[64:65], 0
	v_cvt_scalef32_pk_bf16_fp8 v110, v5, 1.0
	v_cvt_scalef32_pk_bf16_fp8 v111, v5, 1.0 op_sel:[1,0,0]
	v_mfma_f32_4x4x4_16b_bf16 v[76:79], v[106:107], v[64:65], 0
	v_cvt_scalef32_pk_bf16_fp8 v104, v2, 1.0
	v_cvt_scalef32_pk_bf16_fp8 v105, v2, 1.0 op_sel:[1,0,0]
	v_mfma_f32_4x4x4_16b_bf16 v[72:75], v[108:109], v[66:67], v[72:75]
	v_cvt_scalef32_pk_bf16_fp8 v106, v6, 1.0
	v_cvt_scalef32_pk_bf16_fp8 v107, v6, 1.0 op_sel:[1,0,0]
	v_mfma_f32_4x4x4_16b_bf16 v[76:79], v[110:111], v[66:67], v[76:79]
	v_cvt_scalef32_pk_bf16_fp8 v108, v3, 1.0
	v_cvt_scalef32_pk_bf16_fp8 v109, v3, 1.0 op_sel:[1,0,0]
	v_mfma_f32_4x4x4_16b_bf16 v[72:75], v[104:105], v[68:69], v[72:75]
	v_cvt_scalef32_pk_bf16_fp8 v110, v7, 1.0
	v_cvt_scalef32_pk_bf16_fp8 v111, v7, 1.0 op_sel:[1,0,0]
	v_mfma_f32_4x4x4_16b_bf16 v[76:79], v[106:107], v[68:69], v[76:79]
	v_and_or_b32 v112, v112, s2, v240
	v_and_or_b32 v113, v113, s2, v240
	global_load_dwordx4 v[0:3], v112, s[80:81]
	global_load_dwordx4 v[4:7], v113, s[80:81]
	s_waitcnt vmcnt(16)
	v_cvt_scalef32_pk_bf16_fp8 v104, v8, 1.0
	v_cvt_scalef32_pk_bf16_fp8 v105, v8, 1.0 op_sel:[1,0,0]
	v_mfma_f32_4x4x4_16b_bf16 v[72:75], v[108:109], v[70:71], v[72:75]
	v_cvt_scalef32_pk_bf16_fp8 v106, v12, 1.0
	v_cvt_scalef32_pk_bf16_fp8 v107, v12, 1.0 op_sel:[1,0,0]
	v_mfma_f32_4x4x4_16b_bf16 v[76:79], v[110:111], v[70:71], v[76:79]
	v_cvt_scalef32_pk_bf16_fp8 v108, v9, 1.0
	v_cvt_scalef32_pk_bf16_fp8 v109, v9, 1.0 op_sel:[1,0,0]
	v_cvt_scalef32_pk_bf16_fp8 v110, v13, 1.0
	v_cvt_scalef32_pk_bf16_fp8 v111, v13, 1.0 op_sel:[1,0,0]
	v_add_f32_dpp v148, v73, v72 quad_perm:[1,0,3,2] row_mask:0xf bank_mask:0xf
	v_add_f32_dpp v149, v75, v74 quad_perm:[1,0,3,2] row_mask:0xf bank_mask:0xf
	v_add_f32_dpp v150, v76, v77 quad_perm:[1,0,3,2] row_mask:0xf bank_mask:0xf
	v_add_f32_dpp v151, v78, v79 quad_perm:[1,0,3,2] row_mask:0xf bank_mask:0xf
	v_mfma_f32_4x4x4_16b_bf16 v[72:75], v[104:105], v[64:65], 0
	v_add_f32_dpp v88, v149, v148 quad_perm:[2,3,0,1] row_mask:0xf bank_mask:0xf
	v_mfma_f32_4x4x4_16b_bf16 v[76:79], v[106:107], v[64:65], 0
	v_add_f32_dpp v89, v151, v150 quad_perm:[2,3,0,1] row_mask:0xf bank_mask:0xf
	v_cvt_scalef32_pk_bf16_fp8 v104, v10, 1.0
	v_cvt_scalef32_pk_bf16_fp8 v105, v10, 1.0 op_sel:[1,0,0]
	v_mfma_f32_4x4x4_16b_bf16 v[72:75], v[108:109], v[66:67], v[72:75]
	v_cvt_scalef32_pk_bf16_fp8 v106, v14, 1.0
	v_cvt_scalef32_pk_bf16_fp8 v107, v14, 1.0 op_sel:[1,0,0]
	v_mfma_f32_4x4x4_16b_bf16 v[76:79], v[110:111], v[66:67], v[76:79]
	v_cvt_scalef32_pk_bf16_fp8 v108, v11, 1.0
	v_cvt_scalef32_pk_bf16_fp8 v109, v11, 1.0 op_sel:[1,0,0]
	v_mfma_f32_4x4x4_16b_bf16 v[72:75], v[104:105], v[68:69], v[72:75]
	v_cvt_scalef32_pk_bf16_fp8 v110, v15, 1.0
	v_cvt_scalef32_pk_bf16_fp8 v111, v15, 1.0 op_sel:[1,0,0]
	v_mfma_f32_4x4x4_16b_bf16 v[76:79], v[106:107], v[68:69], v[76:79]
	v_and_or_b32 v114, v114, s2, v240
	v_and_or_b32 v115, v115, s2, v240
	global_load_dwordx4 v[8:11], v114, s[80:81]
	global_load_dwordx4 v[12:15], v115, s[80:81]
	s_waitcnt vmcnt(16)
	v_cvt_scalef32_pk_bf16_fp8 v104, v16, 1.0
	v_cvt_scalef32_pk_bf16_fp8 v105, v16, 1.0 op_sel:[1,0,0]
	v_mfma_f32_4x4x4_16b_bf16 v[72:75], v[108:109], v[70:71], v[72:75]
	v_cvt_scalef32_pk_bf16_fp8 v106, v20, 1.0
	v_cvt_scalef32_pk_bf16_fp8 v107, v20, 1.0 op_sel:[1,0,0]
	v_mfma_f32_4x4x4_16b_bf16 v[76:79], v[110:111], v[70:71], v[76:79]
	v_cvt_scalef32_pk_bf16_fp8 v108, v17, 1.0
	v_cvt_scalef32_pk_bf16_fp8 v109, v17, 1.0 op_sel:[1,0,0]
	v_cvt_scalef32_pk_bf16_fp8 v110, v21, 1.0
	v_cvt_scalef32_pk_bf16_fp8 v111, v21, 1.0 op_sel:[1,0,0]
	v_add_f32_dpp v148, v75, v74 quad_perm:[1,0,3,2] row_mask:0xf bank_mask:0xf
	v_add_f32_dpp v149, v73, v72 quad_perm:[1,0,3,2] row_mask:0xf bank_mask:0xf
	v_add_f32_dpp v150, v78, v79 quad_perm:[1,0,3,2] row_mask:0xf bank_mask:0xf
	v_add_f32_dpp v151, v76, v77 quad_perm:[1,0,3,2] row_mask:0xf bank_mask:0xf
	v_mfma_f32_4x4x4_16b_bf16 v[72:75], v[104:105], v[64:65], 0
	v_add_f32_dpp v90, v149, v148 quad_perm:[2,3,0,1] row_mask:0xf bank_mask:0xf
	v_mfma_f32_4x4x4_16b_bf16 v[76:79], v[106:107], v[64:65], 0
	v_add_f32_dpp v91, v151, v150 quad_perm:[2,3,0,1] row_mask:0xf bank_mask:0xf
	v_cvt_scalef32_pk_bf16_fp8 v104, v18, 1.0
	v_cvt_scalef32_pk_bf16_fp8 v105, v18, 1.0 op_sel:[1,0,0]
	v_mfma_f32_4x4x4_16b_bf16 v[72:75], v[108:109], v[66:67], v[72:75]
	v_cvt_scalef32_pk_bf16_fp8 v106, v22, 1.0
	v_cvt_scalef32_pk_bf16_fp8 v107, v22, 1.0 op_sel:[1,0,0]
	v_mfma_f32_4x4x4_16b_bf16 v[76:79], v[110:111], v[66:67], v[76:79]
	v_cvt_scalef32_pk_bf16_fp8 v108, v19, 1.0
	v_cvt_scalef32_pk_bf16_fp8 v109, v19, 1.0 op_sel:[1,0,0]
	v_mfma_f32_4x4x4_16b_bf16 v[72:75], v[104:105], v[68:69], v[72:75]
	v_cvt_scalef32_pk_bf16_fp8 v110, v23, 1.0
	v_cvt_scalef32_pk_bf16_fp8 v111, v23, 1.0 op_sel:[1,0,0]
	v_mfma_f32_4x4x4_16b_bf16 v[76:79], v[106:107], v[68:69], v[76:79]
	v_and_or_b32 v138, v138, s2, v240
	v_and_or_b32 v139, v139, s2, v240
	global_load_dwordx4 v[16:19], v138, s[80:81]
	global_load_dwordx4 v[20:23], v139, s[80:81]
	s_waitcnt vmcnt(16)
	v_cvt_scalef32_pk_bf16_fp8 v104, v24, 1.0
	v_cvt_scalef32_pk_bf16_fp8 v105, v24, 1.0 op_sel:[1,0,0]
	v_mfma_f32_4x4x4_16b_bf16 v[72:75], v[108:109], v[70:71], v[72:75]
	v_cvt_scalef32_pk_bf16_fp8 v106, v28, 1.0
	v_cvt_scalef32_pk_bf16_fp8 v107, v28, 1.0 op_sel:[1,0,0]
	v_mfma_f32_4x4x4_16b_bf16 v[76:79], v[110:111], v[70:71], v[76:79]
	v_cvt_scalef32_pk_bf16_fp8 v108, v25, 1.0
	v_cvt_scalef32_pk_bf16_fp8 v109, v25, 1.0 op_sel:[1,0,0]
	v_cvt_scalef32_pk_bf16_fp8 v110, v29, 1.0
	v_cvt_scalef32_pk_bf16_fp8 v111, v29, 1.0 op_sel:[1,0,0]
	v_add_f32_dpp v148, v73, v72 quad_perm:[1,0,3,2] row_mask:0xf bank_mask:0xf
	v_add_f32_dpp v149, v75, v74 quad_perm:[1,0,3,2] row_mask:0xf bank_mask:0xf
	v_add_f32_dpp v150, v76, v77 quad_perm:[1,0,3,2] row_mask:0xf bank_mask:0xf
	v_add_f32_dpp v151, v78, v79 quad_perm:[1,0,3,2] row_mask:0xf bank_mask:0xf
	v_mfma_f32_4x4x4_16b_bf16 v[72:75], v[104:105], v[64:65], 0
	v_add_f32_dpp v92, v149, v148 quad_perm:[2,3,0,1] row_mask:0xf bank_mask:0xf
	v_mfma_f32_4x4x4_16b_bf16 v[76:79], v[106:107], v[64:65], 0
	v_add_f32_dpp v93, v151, v150 quad_perm:[2,3,0,1] row_mask:0xf bank_mask:0xf
	v_cvt_scalef32_pk_bf16_fp8 v104, v26, 1.0
	v_cvt_scalef32_pk_bf16_fp8 v105, v26, 1.0 op_sel:[1,0,0]
	v_mfma_f32_4x4x4_16b_bf16 v[72:75], v[108:109], v[66:67], v[72:75]
	v_cvt_scalef32_pk_bf16_fp8 v106, v30, 1.0
	v_cvt_scalef32_pk_bf16_fp8 v107, v30, 1.0 op_sel:[1,0,0]
	v_mfma_f32_4x4x4_16b_bf16 v[76:79], v[110:111], v[66:67], v[76:79]
	v_cvt_scalef32_pk_bf16_fp8 v108, v27, 1.0
	v_cvt_scalef32_pk_bf16_fp8 v109, v27, 1.0 op_sel:[1,0,0]
	v_mfma_f32_4x4x4_16b_bf16 v[72:75], v[104:105], v[68:69], v[72:75]
	v_cvt_scalef32_pk_bf16_fp8 v110, v31, 1.0
	v_cvt_scalef32_pk_bf16_fp8 v111, v31, 1.0 op_sel:[1,0,0]
	v_mfma_f32_4x4x4_16b_bf16 v[76:79], v[106:107], v[68:69], v[76:79]
	v_and_or_b32 v140, v140, s2, v240
	v_and_or_b32 v141, v141, s2, v240
	global_load_dwordx4 v[24:27], v140, s[80:81]
	global_load_dwordx4 v[28:31], v141, s[80:81]
	s_waitcnt vmcnt(16)
	v_cvt_scalef32_pk_bf16_fp8 v104, v32, 1.0
	v_cvt_scalef32_pk_bf16_fp8 v105, v32, 1.0 op_sel:[1,0,0]
	v_mfma_f32_4x4x4_16b_bf16 v[72:75], v[108:109], v[70:71], v[72:75]
	v_cvt_scalef32_pk_bf16_fp8 v106, v36, 1.0
	v_cvt_scalef32_pk_bf16_fp8 v107, v36, 1.0 op_sel:[1,0,0]
	v_mfma_f32_4x4x4_16b_bf16 v[76:79], v[110:111], v[70:71], v[76:79]
	v_cvt_scalef32_pk_bf16_fp8 v108, v33, 1.0
	v_cvt_scalef32_pk_bf16_fp8 v109, v33, 1.0 op_sel:[1,0,0]
	v_cvt_scalef32_pk_bf16_fp8 v110, v37, 1.0
	v_cvt_scalef32_pk_bf16_fp8 v111, v37, 1.0 op_sel:[1,0,0]
	v_add_f32_dpp v148, v75, v74 quad_perm:[1,0,3,2] row_mask:0xf bank_mask:0xf
	v_add_f32_dpp v149, v73, v72 quad_perm:[1,0,3,2] row_mask:0xf bank_mask:0xf
	v_add_f32_dpp v150, v78, v79 quad_perm:[1,0,3,2] row_mask:0xf bank_mask:0xf
	v_add_f32_dpp v151, v76, v77 quad_perm:[1,0,3,2] row_mask:0xf bank_mask:0xf
	v_mfma_f32_4x4x4_16b_bf16 v[72:75], v[104:105], v[64:65], 0
	v_add_f32_dpp v94, v149, v148 quad_perm:[2,3,0,1] row_mask:0xf bank_mask:0xf
	v_mfma_f32_4x4x4_16b_bf16 v[76:79], v[106:107], v[64:65], 0
	v_add_f32_dpp v95, v151, v150 quad_perm:[2,3,0,1] row_mask:0xf bank_mask:0xf
	v_cvt_scalef32_pk_bf16_fp8 v104, v34, 1.0
	v_cvt_scalef32_pk_bf16_fp8 v105, v34, 1.0 op_sel:[1,0,0]
	v_mfma_f32_4x4x4_16b_bf16 v[72:75], v[108:109], v[66:67], v[72:75]
	v_cvt_scalef32_pk_bf16_fp8 v106, v38, 1.0
	v_cvt_scalef32_pk_bf16_fp8 v107, v38, 1.0 op_sel:[1,0,0]
	v_mfma_f32_4x4x4_16b_bf16 v[76:79], v[110:111], v[66:67], v[76:79]
	v_cvt_scalef32_pk_bf16_fp8 v108, v35, 1.0
	v_cvt_scalef32_pk_bf16_fp8 v109, v35, 1.0 op_sel:[1,0,0]
	v_mfma_f32_4x4x4_16b_bf16 v[72:75], v[104:105], v[68:69], v[72:75]
	v_cvt_scalef32_pk_bf16_fp8 v110, v39, 1.0
	v_cvt_scalef32_pk_bf16_fp8 v111, v39, 1.0 op_sel:[1,0,0]
	v_mfma_f32_4x4x4_16b_bf16 v[76:79], v[106:107], v[68:69], v[76:79]
	v_and_or_b32 v250, v250, s2, v240
	v_and_or_b32 v251, v251, s2, v240
	global_load_dwordx4 v[32:35], v250, s[80:81]
	global_load_dwordx4 v[36:39], v251, s[80:81]
	s_waitcnt vmcnt(16)
	v_cvt_scalef32_pk_bf16_fp8 v104, v40, 1.0
	v_cvt_scalef32_pk_bf16_fp8 v105, v40, 1.0 op_sel:[1,0,0]
	v_mfma_f32_4x4x4_16b_bf16 v[72:75], v[108:109], v[70:71], v[72:75]
	v_cvt_scalef32_pk_bf16_fp8 v106, v44, 1.0
	v_cvt_scalef32_pk_bf16_fp8 v107, v44, 1.0 op_sel:[1,0,0]
	v_mfma_f32_4x4x4_16b_bf16 v[76:79], v[110:111], v[70:71], v[76:79]
	v_cvt_scalef32_pk_bf16_fp8 v108, v41, 1.0
	v_cvt_scalef32_pk_bf16_fp8 v109, v41, 1.0 op_sel:[1,0,0]
	v_cvt_scalef32_pk_bf16_fp8 v110, v45, 1.0
	v_cvt_scalef32_pk_bf16_fp8 v111, v45, 1.0 op_sel:[1,0,0]
	v_add_f32_dpp v148, v73, v72 quad_perm:[1,0,3,2] row_mask:0xf bank_mask:0xf
	v_add_f32_dpp v149, v75, v74 quad_perm:[1,0,3,2] row_mask:0xf bank_mask:0xf
	v_add_f32_dpp v150, v76, v77 quad_perm:[1,0,3,2] row_mask:0xf bank_mask:0xf
	v_add_f32_dpp v151, v78, v79 quad_perm:[1,0,3,2] row_mask:0xf bank_mask:0xf
	v_mfma_f32_4x4x4_16b_bf16 v[72:75], v[104:105], v[64:65], 0
	v_add_f32_dpp v96, v149, v148 quad_perm:[2,3,0,1] row_mask:0xf bank_mask:0xf
	v_mfma_f32_4x4x4_16b_bf16 v[76:79], v[106:107], v[64:65], 0
	v_add_f32_dpp v97, v151, v150 quad_perm:[2,3,0,1] row_mask:0xf bank_mask:0xf
	v_cvt_scalef32_pk_bf16_fp8 v104, v42, 1.0
	v_cvt_scalef32_pk_bf16_fp8 v105, v42, 1.0 op_sel:[1,0,0]
	v_mfma_f32_4x4x4_16b_bf16 v[72:75], v[108:109], v[66:67], v[72:75]
	v_cvt_scalef32_pk_bf16_fp8 v106, v46, 1.0
	v_cvt_scalef32_pk_bf16_fp8 v107, v46, 1.0 op_sel:[1,0,0]
	v_mfma_f32_4x4x4_16b_bf16 v[76:79], v[110:111], v[66:67], v[76:79]
	v_cvt_scalef32_pk_bf16_fp8 v108, v43, 1.0
	v_cvt_scalef32_pk_bf16_fp8 v109, v43, 1.0 op_sel:[1,0,0]
	v_mfma_f32_4x4x4_16b_bf16 v[72:75], v[104:105], v[68:69], v[72:75]
	v_cvt_scalef32_pk_bf16_fp8 v110, v47, 1.0
	v_cvt_scalef32_pk_bf16_fp8 v111, v47, 1.0 op_sel:[1,0,0]
	v_mfma_f32_4x4x4_16b_bf16 v[76:79], v[106:107], v[68:69], v[76:79]
	v_and_or_b32 v252, v252, s2, v240
	v_and_or_b32 v253, v253, s2, v240
	global_load_dwordx4 v[40:43], v252, s[80:81]
	global_load_dwordx4 v[44:47], v253, s[80:81]
	s_waitcnt vmcnt(16)
; #define PG_ISSUE(BUF, TAB, e0_) do { const int isrc_ = ((e0_) < 64) ? myi0 : myi1; \
;       _Pragma("unroll") for (int e = 0; e < 8; ++e) { const int idx_ = __builtin_amdgcn_readlane(isrc_, ((e0_) + e) & 63); \
;         BUF[e] = *(const u32x4*)((TAB) + (size_t)idx_ * 1024 + lane * 16); } } while (0)
; DEV void peer_gather(const Params& P, int l, int m0, const int* idxs, const float* gs) {
;     ...
;     PG_ISSUE(b0, U, 0);
; #pragma nounroll
;     for (int e0 = 0; e0 < 128; e0 += 16) {
;       PG_ISSUE(b1, U, e0 + 8);
;       PG_U8(b0, 0, e0);
;       if (e0 + 16 < 128) PG_ISSUE(b0, U, e0 + 16); else PG_ISSUE(b0, V, 0);
;       PG_U8(b1, 0, e0 + 8);
	v_cvt_scalef32_pk_bf16_fp8 v104, v48, 1.0
	v_cvt_scalef32_pk_bf16_fp8 v105, v48, 1.0 op_sel:[1,0,0]
	v_mfma_f32_4x4x4_16b_bf16 v[72:75], v[108:109], v[70:71], v[72:75]
	v_cvt_scalef32_pk_bf16_fp8 v106, v52, 1.0
	v_cvt_scalef32_pk_bf16_fp8 v107, v52, 1.0 op_sel:[1,0,0]
	v_mfma_f32_4x4x4_16b_bf16 v[76:79], v[110:111], v[70:71], v[76:79]
	v_cvt_scalef32_pk_bf16_fp8 v108, v49, 1.0
	v_cvt_scalef32_pk_bf16_fp8 v109, v49, 1.0 op_sel:[1,0,0]
	v_cvt_scalef32_pk_bf16_fp8 v110, v53, 1.0
	v_cvt_scalef32_pk_bf16_fp8 v111, v53, 1.0 op_sel:[1,0,0]
	v_add_f32_dpp v148, v75, v74 quad_perm:[1,0,3,2] row_mask:0xf bank_mask:0xf
	v_add_f32_dpp v149, v73, v72 quad_perm:[1,0,3,2] row_mask:0xf bank_mask:0xf
	v_add_f32_dpp v150, v78, v79 quad_perm:[1,0,3,2] row_mask:0xf bank_mask:0xf
	v_add_f32_dpp v151, v76, v77 quad_perm:[1,0,3,2] row_mask:0xf bank_mask:0xf
	v_mfma_f32_4x4x4_16b_bf16 v[72:75], v[104:105], v[64:65], 0
	v_add_f32_dpp v98, v149, v148 quad_perm:[2,3,0,1] row_mask:0xf bank_mask:0xf
	v_mfma_f32_4x4x4_16b_bf16 v[76:79], v[106:107], v[64:65], 0
	v_add_f32_dpp v99, v151, v150 quad_perm:[2,3,0,1] row_mask:0xf bank_mask:0xf
	v_cvt_scalef32_pk_bf16_fp8 v104, v50, 1.0
	v_cvt_scalef32_pk_bf16_fp8 v105, v50, 1.0 op_sel:[1,0,0]
	v_mfma_f32_4x4x4_16b_bf16 v[72:75], v[108:109], v[66:67], v[72:75]
	v_cvt_scalef32_pk_bf16_fp8 v106, v54, 1.0
	v_cvt_scalef32_pk_bf16_fp8 v107, v54, 1.0 op_sel:[1,0,0]
	v_mfma_f32_4x4x4_16b_bf16 v[76:79], v[110:111], v[66:67], v[76:79]
	v_cvt_scalef32_pk_bf16_fp8 v108, v51, 1.0
	v_cvt_scalef32_pk_bf16_fp8 v109, v51, 1.0 op_sel:[1,0,0]
	v_mfma_f32_4x4x4_16b_bf16 v[72:75], v[104:105], v[68:69], v[72:75]
	v_cvt_scalef32_pk_bf16_fp8 v110, v55, 1.0
	v_cvt_scalef32_pk_bf16_fp8 v111, v55, 1.0 op_sel:[1,0,0]
	v_mfma_f32_4x4x4_16b_bf16 v[76:79], v[106:107], v[68:69], v[76:79]
	v_and_or_b32 v242, v242, s2, v240
	v_and_or_b32 v243, v243, s2, v240
	global_load_dwordx4 v[48:51], v242, s[80:81]
	global_load_dwordx4 v[52:55], v243, s[80:81]
	s_waitcnt vmcnt(16)
	v_cvt_scalef32_pk_bf16_fp8 v104, v56, 1.0
	v_cvt_scalef32_pk_bf16_fp8 v105, v56, 1.0 op_sel:[1,0,0]
	v_mfma_f32_4x4x4_16b_bf16 v[72:75], v[108:109], v[70:71], v[72:75]
	v_cvt_scalef32_pk_bf16_fp8 v106, v60, 1.0
	v_cvt_scalef32_pk_bf16_fp8 v107, v60, 1.0 op_sel:[1,0,0]
	v_mfma_f32_4x4x4_16b_bf16 v[76:79], v[110:111], v[70:71], v[76:79]
	v_cvt_scalef32_pk_bf16_fp8 v108, v57, 1.0
	v_cvt_scalef32_pk_bf16_fp8 v109, v57, 1.0 op_sel:[1,0,0]
	v_cvt_scalef32_pk_bf16_fp8 v110, v61, 1.0
	v_cvt_scalef32_pk_bf16_fp8 v111, v61, 1.0 op_sel:[1,0,0]
	v_add_f32_dpp v148, v73, v72 quad_perm:[1,0,3,2] row_mask:0xf bank_mask:0xf
	v_add_f32_dpp v149, v75, v74 quad_perm:[1,0,3,2] row_mask:0xf bank_mask:0xf
	v_add_f32_dpp v150, v76, v77 quad_perm:[1,0,3,2] row_mask:0xf bank_mask:0xf
	v_add_f32_dpp v151, v78, v79 quad_perm:[1,0,3,2] row_mask:0xf bank_mask:0xf
	v_mfma_f32_4x4x4_16b_bf16 v[72:75], v[104:105], v[64:65], 0
	v_add_f32_dpp v100, v149, v148 quad_perm:[2,3,0,1] row_mask:0xf bank_mask:0xf
	v_mfma_f32_4x4x4_16b_bf16 v[76:79], v[106:107], v[64:65], 0
	v_add_f32_dpp v101, v151, v150 quad_perm:[2,3,0,1] row_mask:0xf bank_mask:0xf
	v_cvt_scalef32_pk_bf16_fp8 v104, v58, 1.0
	v_cvt_scalef32_pk_bf16_fp8 v105, v58, 1.0 op_sel:[1,0,0]
	v_mfma_f32_4x4x4_16b_bf16 v[72:75], v[108:109], v[66:67], v[72:75]
	v_cvt_scalef32_pk_bf16_fp8 v106, v62, 1.0
	v_cvt_scalef32_pk_bf16_fp8 v107, v62, 1.0 op_sel:[1,0,0]
	v_mfma_f32_4x4x4_16b_bf16 v[76:79], v[110:111], v[66:67], v[76:79]
	v_cvt_scalef32_pk_bf16_fp8 v108, v59, 1.0
	v_cvt_scalef32_pk_bf16_fp8 v109, v59, 1.0 op_sel:[1,0,0]
	v_mfma_f32_4x4x4_16b_bf16 v[72:75], v[104:105], v[68:69], v[72:75]
	v_cvt_scalef32_pk_bf16_fp8 v110, v63, 1.0
	v_cvt_scalef32_pk_bf16_fp8 v111, v63, 1.0 op_sel:[1,0,0]
	v_mfma_f32_4x4x4_16b_bf16 v[76:79], v[106:107], v[68:69], v[76:79]
	v_and_or_b32 v244, v244, s2, v240
	v_and_or_b32 v245, v245, s2, v240
	global_load_dwordx4 v[56:59], v244, s[80:81]
	global_load_dwordx4 v[60:63], v245, s[80:81]
	v_mfma_f32_4x4x4_16b_bf16 v[72:75], v[108:109], v[70:71], v[72:75]
	v_mfma_f32_4x4x4_16b_bf16 v[76:79], v[110:111], v[70:71], v[76:79]
	s_add_u32 s92, s100, 2
	s_and_b32 s92, s92, 15
	v_lshl_add_u32 v116, s92, 9, v246
	ds_read_b128 v[112:115], v116
	ds_read_b128 v[138:141], v116 offset:16
	ds_read_b128 v[250:253], v116 offset:32
	ds_read_b128 v[242:245], v116 offset:48
	v_lshl_add_u32 v117, s98, 9, v247
	ds_read_b32 v136, v117
	ds_read_b32 v137, v117 offset:32
	v_add_f32_dpp v148, v75, v74 quad_perm:[1,0,3,2] row_mask:0xf bank_mask:0xf
	v_add_f32_dpp v149, v73, v72 quad_perm:[1,0,3,2] row_mask:0xf bank_mask:0xf
	v_add_f32_dpp v150, v78, v79 quad_perm:[1,0,3,2] row_mask:0xf bank_mask:0xf
	v_add_f32_dpp v151, v76, v77 quad_perm:[1,0,3,2] row_mask:0xf bank_mask:0xf
	v_add_f32_dpp v102, v149, v148 quad_perm:[2,3,0,1] row_mask:0xf bank_mask:0xf
	s_nop 0
	v_add_f32_dpp v103, v151, v150 quad_perm:[2,3,0,1] row_mask:0xf bank_mask:0xf
	v_cndmask_b32_e64 v144, v88, v89, s[88:89]
	v_cndmask_b32_e64 v145, v90, v91, s[88:89]
	v_cndmask_b32_e64 v88, v144, v145, s[86:87]
	v_cndmask_b32_e64 v144, v92, v93, s[88:89]
	v_cndmask_b32_e64 v145, v94, v95, s[88:89]
	v_cndmask_b32_e64 v92, v144, v145, s[86:87]
	v_cndmask_b32_e64 v144, v96, v97, s[88:89]
	v_cndmask_b32_e64 v145, v98, v99, s[88:89]
	v_cndmask_b32_e64 v96, v144, v145, s[86:87]
	v_cndmask_b32_e64 v144, v100, v101, s[88:89]
	v_cndmask_b32_e64 v145, v102, v103, s[88:89]
	v_cndmask_b32_e64 v100, v144, v145, s[86:87]
	v_cndmask_b32_e64 v144, v88, v92, s[90:91]
	v_cndmask_b32_e64 v145, v92, v88, s[90:91]
	v_cndmask_b32_e64 v146, v96, v100, s[90:91]
	v_cndmask_b32_e64 v147, v100, v96, s[90:91]
	s_nop 1
	v_add_f32_dpp v88, v145, v144 row_shl:4 row_mask:0xf bank_mask:0x5
	v_add_f32_dpp v88, v145, v144 row_shr:4 row_mask:0xf bank_mask:0xa
	v_add_f32_dpp v96, v147, v146 row_shl:4 row_mask:0xf bank_mask:0x5
	v_add_f32_dpp v96, v147, v146 row_shr:4 row_mask:0xf bank_mask:0xa
	s_waitcnt lgkmcnt(0)
	v_add_f32_e32 v136, v136, v88
	v_add_f32_e32 v137, v137, v96
	ds_write_b32 v117, v136
	ds_write_b32 v117, v137 offset:32
	s_add_u32 s100, s100, 1
	s_cmp_lt_u32 s100, 128
	s_cbranch_scc1 .Lpg0_uloop
	s_waitcnt vmcnt(0) lgkmcnt(0)
	s_mov_b32 s2, 0
.Lpg0_act:
	v_readlane_b32 s82, v231, 28
	v_readlane_b32 s83, v231, 29
	s_nop 4
	s_lshl_b32 s98, s2, 11
	s_add_u32 s98, s98, s101
	v_add_u32_e32 v116, s98, v234
	v_add_u32_e32 v117, 0x10000, v116
	ds_read_b32 v0, v116 offset:0
	ds_read_b32 v8, v117 offset:0
	ds_read_b32 v1, v116 offset:256
	ds_read_b32 v9, v117 offset:256
	ds_read_b32 v2, v116 offset:512
	ds_read_b32 v10, v117 offset:512
	ds_read_b32 v3, v116 offset:768
	ds_read_b32 v11, v117 offset:768
	ds_read_b32 v4, v116 offset:1024
	ds_read_b32 v12, v117 offset:1024
	ds_read_b32 v5, v116 offset:1280
	ds_read_b32 v13, v117 offset:1280
	ds_read_b32 v6, v116 offset:1536
	ds_read_b32 v14, v117 offset:1536
	ds_read_b32 v7, v116 offset:1792
	ds_read_b32 v15, v117 offset:1792
	s_waitcnt lgkmcnt(0)
	s_lshl_b32 s99, s2, 2
	s_add_u32 s99, s99, s33
	s_add_u32 s99, s99, 0
	s_lshl_b32 s99, s99, 9
	v_and_b32_e32 v0, 0x7f, v0
	v_lshl_add_u32 v0, v0, 2, s99
	global_load_dword v16, v0, s[82:83]
	v_and_b32_e32 v1, 0x7f, v1
	v_lshl_add_u32 v1, v1, 2, s99
	global_load_dword v17, v1, s[82:83]
	s_lshl_b32 s99, s2, 2
	s_add_u32 s99, s99, s33
	s_add_u32 s99, s99, 1
	s_lshl_b32 s99, s99, 9
	v_and_b32_e32 v2, 0x7f, v2
	v_lshl_add_u32 v2, v2, 2, s99
	global_load_dword v18, v2, s[82:83]
	v_and_b32_e32 v3, 0x7f, v3
	v_lshl_add_u32 v3, v3, 2, s99
	global_load_dword v19, v3, s[82:83]
	s_lshl_b32 s99, s2, 2
	s_add_u32 s99, s99, s33
	s_add_u32 s99, s99, 2
	s_lshl_b32 s99, s99, 9
	v_and_b32_e32 v4, 0x7f, v4
	v_lshl_add_u32 v4, v4, 2, s99
	global_load_dword v20, v4, s[82:83]
	v_and_b32_e32 v5, 0x7f, v5
	v_lshl_add_u32 v5, v5, 2, s99
	global_load_dword v21, v5, s[82:83]
	s_lshl_b32 s99, s2, 2
	s_add_u32 s99, s99, s33
	s_add_u32 s99, s99, 3
	s_lshl_b32 s99, s99, 9
	v_and_b32_e32 v6, 0x7f, v6
	v_lshl_add_u32 v6, v6, 2, s99
	global_load_dword v22, v6, s[82:83]
	v_and_b32_e32 v7, 0x7f, v7
	v_lshl_add_u32 v7, v7, 2, s99
	global_load_dword v23, v7, s[82:83]
	v_mul_f32_e32 v8, 0x3c800000, v8
	v_mul_f32_e32 v9, 0x3c800000, v9
	v_mul_f32_e32 v10, 0x3c800000, v10
	v_mul_f32_e32 v11, 0x3c800000, v11
	v_mul_f32_e32 v12, 0x3c800000, v12
	v_mul_f32_e32 v13, 0x3c800000, v13
	v_mul_f32_e32 v14, 0x3c800000, v14
	v_mul_f32_e32 v15, 0x3c800000, v15
	v_mul_f32_e32 v24, 0x3d372713, v8
	v_mul_f32_e32 v25, 0x3d372713, v9
	v_mul_f32_e32 v26, 0x3d372713, v10
	v_mul_f32_e32 v27, 0x3d372713, v11
	v_mul_f32_e32 v28, 0x3d372713, v12
	v_mul_f32_e32 v29, 0x3d372713, v13
	v_mul_f32_e32 v30, 0x3d372713, v14
	v_mul_f32_e32 v31, 0x3d372713, v15
	v_mul_f32_e32 v24, v8, v24
	v_mul_f32_e32 v25, v9, v25
	v_mul_f32_e32 v26, v10, v26
	v_mul_f32_e32 v27, v11, v27
	v_mul_f32_e32 v28, v12, v28
	v_mul_f32_e32 v29, v13, v29
	v_mul_f32_e32 v30, v14, v30
	v_mul_f32_e32 v31, v15, v31
	v_fma_f32 v24, v8, v24, v8
	v_fma_f32 v25, v9, v25, v9
	v_fma_f32 v26, v10, v26, v10
	v_fma_f32 v27, v11, v27, v11
	v_fma_f32 v28, v12, v28, v12
	v_fma_f32 v29, v13, v29, v13
	v_fma_f32 v30, v14, v30, v14
	v_fma_f32 v31, v15, v31, v15
	v_mul_f32_e32 v24, 0xbfcc422a, v24
	v_mul_f32_e32 v25, 0xbfcc422a, v25
	v_mul_f32_e32 v26, 0xbfcc422a, v26
	v_mul_f32_e32 v27, 0xbfcc422a, v27
	v_mul_f32_e32 v28, 0xbfcc422a, v28
	v_mul_f32_e32 v29, 0xbfcc422a, v29
	v_mul_f32_e32 v30, 0xbfcc422a, v30
	v_mul_f32_e32 v31, 0xbfcc422a, v31
	v_mul_f32_e32 v24, 0x3fb8aa3b, v24
	v_mul_f32_e32 v25, 0x3fb8aa3b, v25
	v_mul_f32_e32 v26, 0x3fb8aa3b, v26
	v_mul_f32_e32 v27, 0x3fb8aa3b, v27
	v_mul_f32_e32 v28, 0x3fb8aa3b, v28
	v_mul_f32_e32 v29, 0x3fb8aa3b, v29
	v_mul_f32_e32 v30, 0x3fb8aa3b, v30
	v_mul_f32_e32 v31, 0x3fb8aa3b, v31
	v_exp_f32_e32 v24, v24
	v_exp_f32_e32 v25, v25
	v_exp_f32_e32 v26, v26
	v_exp_f32_e32 v27, v27
	v_exp_f32_e32 v28, v28
	v_exp_f32_e32 v29, v29
	v_exp_f32_e32 v30, v30
	v_exp_f32_e32 v31, v31
	s_nop 0
	v_add_f32_e32 v24, 1.0, v24
	v_add_f32_e32 v25, 1.0, v25
	v_add_f32_e32 v26, 1.0, v26
	v_add_f32_e32 v27, 1.0, v27
	v_add_f32_e32 v28, 1.0, v28
	v_add_f32_e32 v29, 1.0, v29
	v_add_f32_e32 v30, 1.0, v30
	v_add_f32_e32 v31, 1.0, v31
	v_rcp_f32_e32 v24, v24
	v_rcp_f32_e32 v25, v25
	v_rcp_f32_e32 v26, v26
	v_rcp_f32_e32 v27, v27
	v_rcp_f32_e32 v28, v28
	v_rcp_f32_e32 v29, v29
	v_rcp_f32_e32 v30, v30
	v_rcp_f32_e32 v31, v31
	s_nop 0
	v_mul_f32_e32 v24, v8, v24
	v_mul_f32_e32 v25, v9, v25
	v_mul_f32_e32 v26, v10, v26
	v_mul_f32_e32 v27, v11, v27
	v_mul_f32_e32 v28, v12, v28
	v_mul_f32_e32 v29, v13, v29
	v_mul_f32_e32 v30, v14, v30
	v_mul_f32_e32 v31, v15, v31
	s_waitcnt vmcnt(0)
	v_mul_f32_e32 v24, v24, v16
	ds_write_b32 v117, v24 offset:0
	v_mul_f32_e32 v25, v25, v17
	ds_write_b32 v117, v25 offset:256
	v_mul_f32_e32 v26, v26, v18
	ds_write_b32 v117, v26 offset:512
	v_mul_f32_e32 v27, v27, v19
	ds_write_b32 v117, v27 offset:768
	v_mul_f32_e32 v28, v28, v20
	ds_write_b32 v117, v28 offset:1024
	v_mul_f32_e32 v29, v29, v21
	ds_write_b32 v117, v29 offset:1280
	v_mul_f32_e32 v30, v30, v22
	ds_write_b32 v117, v30 offset:1536
	v_mul_f32_e32 v31, v31, v23
	ds_write_b32 v117, v31 offset:1792
	s_add_u32 s2, s2, 1
	s_cmp_lt_u32 s2, 4
	s_cbranch_scc1 .Lpg0_act
; #define PG_ISSUE(BUF, TAB, e0_) do { const int isrc_ = ((e0_) < 64) ? myi0 : myi1; \
;       _Pragma("unroll") for (int e = 0; e < 8; ++e) { const int idx_ = __builtin_amdgcn_readlane(isrc_, ((e0_) + e) & 63); \
;         BUF[e] = *(const u32x4*)((TAB) + (size_t)idx_ * 1024 + lane * 16); } } while (0)
; DEV void peer_gather(const Params& P, int l, int m0, const int* idxs, const float* gs) {
;     ...
;     PG_ISSUE(b0, U, 0);
; #pragma nounroll
;     for (int e0 = 0; e0 < 128; e0 += 16) {
;       PG_ISSUE(b1, U, e0 + 8);
;       PG_U8(b0, 0, e0);
;       if (e0 + 16 < 128) PG_ISSUE(b0, U, e0 + 16); else PG_ISSUE(b0, V, 0);
;       PG_U8(b1, 0, e0 + 8);
;     }
;     float* hrow = P.out + tok * DM + lane * 16;
;     f32x4 hv[4];
; #pragma unroll
;     for (int q = 0; q < 4; ++q) hv[q] = *(const f32x4*)(hrow + 4 * q);
;     if (i + 1 < 16) {
;       const int tn = tt + 1;
;       nxa = *(const u32x4*)(hn + (size_t)(m0 + tn) * DM + lane * 16); nxb = *(const u32x4*)(hn + (size_t)(m0 + tn) * DM + lane * 16 + 8);
;       ni0 = idxs[tn * 128 + lane]; ni1 = idxs[tn * 128 + 64 + lane]; ng0 = gs[tn * 128 + lane]; ng1 = gs[tn * 128 + 64 + lane];
;     }
; #pragma nounroll
;     for (int e0 = 0; e0 < 128; e0 += 16) {
;       PG_ISSUE(b1, V, e0 + 8);
;       if (e0 == 64 && i + 1 < 16) sort_lists(lane, ni0, ni1, ng0, ng1);
;       PG_V16(b0, e0);
;       if (e0 + 16 < 128) PG_ISSUE(b0, V, e0 + 16);
;       PG_V16(b1, e0 + 8);
	s_waitcnt lgkmcnt(0)
	v_readfirstlane_b32 s80, v126
	v_readfirstlane_b32 s81, v127
	s_nop 4
	v_readfirstlane_b32 s82, v132
	v_readfirstlane_b32 s83, v133
	s_nop 4
	s_mov_b32 s2, 0xffffff80
	s_lshl_b32 vcc_lo, s3, 12
	s_add_u32 s82, s82, vcc_lo
	s_addc_u32 s83, s83, 0
	s_mov_b32 s88, 0xff00ff00
	s_mov_b32 s89, 0xff00ff00
	v_lshl_add_u32 v246, v237, 4, s101
	v_add_u32_e32 v247, 0x10000, v246
	v_lshlrev_b32_e32 v238, 2, v235
	v_bfe_u32 v116, v233, 5, 1
	v_lshl_add_u32 v238, v116, 3, v238
	v_bfe_u32 v116, v233, 4, 1
	v_lshl_add_u32 v238, v116, 4, v238
	v_bfe_u32 v116, v233, 3, 1
	v_lshl_add_u32 v238, v116, 5, v238
	s_mov_b32 s100, 0
	s_mov_b32 s98, 0
	s_mov_b32 s99, 0
	v_lshl_add_u32 v116, s98, 9, v246
	ds_read_b128 v[112:115], v116
	ds_read_b128 v[138:141], v116 offset:16
	ds_read_b128 v[250:253], v116 offset:32
	ds_read_b128 v[242:245], v116 offset:48
	v_lshl_or_b32 v240, s99, 21, v235
	s_waitcnt lgkmcnt(0)
	v_and_or_b32 v112, v112, s2, v240
	v_and_or_b32 v113, v113, s2, v240
	global_load_dwordx4 v[0:3], v112, s[80:81]
	global_load_dwordx4 v[4:7], v113, s[80:81]
	v_and_or_b32 v114, v114, s2, v240
	v_and_or_b32 v115, v115, s2, v240
	global_load_dwordx4 v[8:11], v114, s[80:81]
	global_load_dwordx4 v[12:15], v115, s[80:81]
	v_and_or_b32 v138, v138, s2, v240
	v_and_or_b32 v139, v139, s2, v240
	global_load_dwordx4 v[16:19], v138, s[80:81]
	global_load_dwordx4 v[20:23], v139, s[80:81]
	v_and_or_b32 v140, v140, s2, v240
	v_and_or_b32 v141, v141, s2, v240
	global_load_dwordx4 v[24:27], v140, s[80:81]
	global_load_dwordx4 v[28:31], v141, s[80:81]
	v_and_or_b32 v250, v250, s2, v240
	v_and_or_b32 v251, v251, s2, v240
	global_load_dwordx4 v[32:35], v250, s[80:81]
	global_load_dwordx4 v[36:39], v251, s[80:81]
	v_and_or_b32 v252, v252, s2, v240
	v_and_or_b32 v253, v253, s2, v240
	global_load_dwordx4 v[40:43], v252, s[80:81]
	global_load_dwordx4 v[44:47], v253, s[80:81]
	v_and_or_b32 v242, v242, s2, v240
	v_and_or_b32 v243, v243, s2, v240
	global_load_dwordx4 v[48:51], v242, s[80:81]
	global_load_dwordx4 v[52:55], v243, s[80:81]
	v_and_or_b32 v244, v244, s2, v240
	v_and_or_b32 v245, v245, s2, v240
	global_load_dwordx4 v[56:59], v244, s[80:81]
	global_load_dwordx4 v[60:63], v245, s[80:81]
	s_mov_b32 s92, 1
	v_lshl_add_u32 v116, s92, 9, v246
	ds_read_b128 v[112:115], v116
	ds_read_b128 v[138:141], v116 offset:16
	ds_read_b128 v[250:253], v116 offset:32
	ds_read_b128 v[242:245], v116 offset:48
	v_lshl_add_u32 v117, s98, 9, v247
	ds_read_b128 v[84:87], v117
	ds_read_b128 v[88:91], v117 offset:16
	ds_read_b128 v[92:95], v117 offset:32
	ds_read_b128 v[96:99], v117 offset:48
	s_mov_b32 s98, 0
	s_mov_b32 s99, 0
	s_lshl3_add_u32 vcc_lo, s98, s99
	v_lshl_add_u32 v119, vcc_lo, 9, v238
	global_load_dwordx2 v[80:81], v119, s[82:83]
	s_waitcnt vmcnt(0)
.Lpg0_vloop:
	s_barrier
	s_add_u32 s98, s100, 1
	s_min_u32 s98, s98, 127
	s_lshr_b32 s93, s98, 4
	s_and_b32 s98, s98, 15
	s_lshl3_add_u32 vcc_lo, s98, s93
	v_lshl_add_u32 v152, vcc_lo, 9, v238
	global_load_dwordx2 v[82:83], v152, s[82:83]
	v_lshl_or_b32 v240, s93, 21, v235
	s_waitcnt lgkmcnt(0)
	s_waitcnt vmcnt(16)
	v_cvt_pk_f32_fp8_e32 v[104:105], v0
	v_cvt_pk_f32_fp8_e32 v[108:109], v4
	v_cvt_pk_f32_fp8_sdwa v[106:107], v0 src0_sel:WORD_1
	v_cvt_pk_f32_fp8_sdwa v[110:111], v4 src0_sel:WORD_1
	v_pk_mul_f32 v[64:65], v[104:105], v[84:85] op_sel_hi:[1,0]
	v_pk_mul_f32 v[66:67], v[106:107], v[84:85] op_sel_hi:[1,0]
	v_pk_fma_f32 v[64:65], v[108:109], v[84:85], v[64:65] op_sel:[0,1,0] op_sel_hi:[1,1,1]
	v_pk_fma_f32 v[66:67], v[110:111], v[84:85], v[66:67] op_sel:[0,1,0] op_sel_hi:[1,1,1]
	v_cvt_pk_f32_fp8_e32 v[104:105], v1
	v_cvt_pk_f32_fp8_e32 v[108:109], v5
	v_cvt_pk_f32_fp8_sdwa v[106:107], v1 src0_sel:WORD_1
	v_cvt_pk_f32_fp8_sdwa v[110:111], v5 src0_sel:WORD_1
	v_pk_mul_f32 v[68:69], v[104:105], v[84:85] op_sel_hi:[1,0]
	v_pk_mul_f32 v[70:71], v[106:107], v[84:85] op_sel_hi:[1,0]
	v_pk_fma_f32 v[68:69], v[108:109], v[84:85], v[68:69] op_sel:[0,1,0] op_sel_hi:[1,1,1]
	v_pk_fma_f32 v[70:71], v[110:111], v[84:85], v[70:71] op_sel:[0,1,0] op_sel_hi:[1,1,1]
	v_cvt_pk_f32_fp8_e32 v[104:105], v2
	v_cvt_pk_f32_fp8_e32 v[108:109], v6
	v_cvt_pk_f32_fp8_sdwa v[106:107], v2 src0_sel:WORD_1
	v_cvt_pk_f32_fp8_sdwa v[110:111], v6 src0_sel:WORD_1
	v_pk_mul_f32 v[72:73], v[104:105], v[84:85] op_sel_hi:[1,0]
	v_pk_mul_f32 v[74:75], v[106:107], v[84:85] op_sel_hi:[1,0]
	v_pk_fma_f32 v[72:73], v[108:109], v[84:85], v[72:73] op_sel:[0,1,0] op_sel_hi:[1,1,1]
	v_pk_fma_f32 v[74:75], v[110:111], v[84:85], v[74:75] op_sel:[0,1,0] op_sel_hi:[1,1,1]
	v_cvt_pk_f32_fp8_e32 v[104:105], v3
	v_cvt_pk_f32_fp8_e32 v[108:109], v7
	v_cvt_pk_f32_fp8_sdwa v[106:107], v3 src0_sel:WORD_1
	v_cvt_pk_f32_fp8_sdwa v[110:111], v7 src0_sel:WORD_1
	v_pk_mul_f32 v[76:77], v[104:105], v[84:85] op_sel_hi:[1,0]
	v_pk_mul_f32 v[78:79], v[106:107], v[84:85] op_sel_hi:[1,0]
	v_and_or_b32 v112, v112, s2, v240
	v_and_or_b32 v113, v113, s2, v240
	global_load_dwordx4 v[0:3], v112, s[80:81]
	global_load_dwordx4 v[4:7], v113, s[80:81]
	v_pk_fma_f32 v[76:77], v[108:109], v[84:85], v[76:77] op_sel:[0,1,0] op_sel_hi:[1,1,1]
	v_pk_fma_f32 v[78:79], v[110:111], v[84:85], v[78:79] op_sel:[0,1,0] op_sel_hi:[1,1,1]
	s_waitcnt vmcnt(16)
	v_cvt_pk_f32_fp8_e32 v[104:105], v8
	v_cvt_pk_f32_fp8_e32 v[108:109], v12
	v_cvt_pk_f32_fp8_sdwa v[106:107], v8 src0_sel:WORD_1
	v_cvt_pk_f32_fp8_sdwa v[110:111], v12 src0_sel:WORD_1
	v_pk_fma_f32 v[64:65], v[104:105], v[86:87], v[64:65] op_sel_hi:[1,0,1]
	v_pk_fma_f32 v[66:67], v[106:107], v[86:87], v[66:67] op_sel_hi:[1,0,1]
	v_pk_fma_f32 v[64:65], v[108:109], v[86:87], v[64:65] op_sel:[0,1,0] op_sel_hi:[1,1,1]
	v_pk_fma_f32 v[66:67], v[110:111], v[86:87], v[66:67] op_sel:[0,1,0] op_sel_hi:[1,1,1]
	v_cvt_pk_f32_fp8_e32 v[104:105], v9
	v_cvt_pk_f32_fp8_e32 v[108:109], v13
	v_cvt_pk_f32_fp8_sdwa v[106:107], v9 src0_sel:WORD_1
	v_cvt_pk_f32_fp8_sdwa v[110:111], v13 src0_sel:WORD_1
	v_pk_fma_f32 v[68:69], v[104:105], v[86:87], v[68:69] op_sel_hi:[1,0,1]
	v_pk_fma_f32 v[70:71], v[106:107], v[86:87], v[70:71] op_sel_hi:[1,0,1]
	v_pk_fma_f32 v[68:69], v[108:109], v[86:87], v[68:69] op_sel:[0,1,0] op_sel_hi:[1,1,1]
	v_pk_fma_f32 v[70:71], v[110:111], v[86:87], v[70:71] op_sel:[0,1,0] op_sel_hi:[1,1,1]
	v_cvt_pk_f32_fp8_e32 v[104:105], v10
	v_cvt_pk_f32_fp8_e32 v[108:109], v14
	v_cvt_pk_f32_fp8_sdwa v[106:107], v10 src0_sel:WORD_1
	v_cvt_pk_f32_fp8_sdwa v[110:111], v14 src0_sel:WORD_1
	v_pk_fma_f32 v[72:73], v[104:105], v[86:87], v[72:73] op_sel_hi:[1,0,1]
	v_pk_fma_f32 v[74:75], v[106:107], v[86:87], v[74:75] op_sel_hi:[1,0,1]
	v_pk_fma_f32 v[72:73], v[108:109], v[86:87], v[72:73] op_sel:[0,1,0] op_sel_hi:[1,1,1]
	v_pk_fma_f32 v[74:75], v[110:111], v[86:87], v[74:75] op_sel:[0,1,0] op_sel_hi:[1,1,1]
	v_cvt_pk_f32_fp8_e32 v[104:105], v11
	v_cvt_pk_f32_fp8_e32 v[108:109], v15
	v_cvt_pk_f32_fp8_sdwa v[106:107], v11 src0_sel:WORD_1
	v_cvt_pk_f32_fp8_sdwa v[110:111], v15 src0_sel:WORD_1
	v_pk_fma_f32 v[76:77], v[104:105], v[86:87], v[76:77] op_sel_hi:[1,0,1]
	v_pk_fma_f32 v[78:79], v[106:107], v[86:87], v[78:79] op_sel_hi:[1,0,1]
	v_and_or_b32 v114, v114, s2, v240
	v_and_or_b32 v115, v115, s2, v240
	global_load_dwordx4 v[8:11], v114, s[80:81]
	global_load_dwordx4 v[12:15], v115, s[80:81]
	v_pk_fma_f32 v[76:77], v[108:109], v[86:87], v[76:77] op_sel:[0,1,0] op_sel_hi:[1,1,1]
	v_pk_fma_f32 v[78:79], v[110:111], v[86:87], v[78:79] op_sel:[0,1,0] op_sel_hi:[1,1,1]
	s_waitcnt vmcnt(16)
	v_cvt_pk_f32_fp8_e32 v[104:105], v16
	v_cvt_pk_f32_fp8_e32 v[108:109], v20
	v_cvt_pk_f32_fp8_sdwa v[106:107], v16 src0_sel:WORD_1
	v_cvt_pk_f32_fp8_sdwa v[110:111], v20 src0_sel:WORD_1
	v_pk_fma_f32 v[64:65], v[104:105], v[88:89], v[64:65] op_sel_hi:[1,0,1]
	v_pk_fma_f32 v[66:67], v[106:107], v[88:89], v[66:67] op_sel_hi:[1,0,1]
	v_pk_fma_f32 v[64:65], v[108:109], v[88:89], v[64:65] op_sel:[0,1,0] op_sel_hi:[1,1,1]
	v_pk_fma_f32 v[66:67], v[110:111], v[88:89], v[66:67] op_sel:[0,1,0] op_sel_hi:[1,1,1]
	v_cvt_pk_f32_fp8_e32 v[104:105], v17
	v_cvt_pk_f32_fp8_e32 v[108:109], v21
	v_cvt_pk_f32_fp8_sdwa v[106:107], v17 src0_sel:WORD_1
	v_cvt_pk_f32_fp8_sdwa v[110:111], v21 src0_sel:WORD_1
	v_pk_fma_f32 v[68:69], v[104:105], v[88:89], v[68:69] op_sel_hi:[1,0,1]
	v_pk_fma_f32 v[70:71], v[106:107], v[88:89], v[70:71] op_sel_hi:[1,0,1]
	v_pk_fma_f32 v[68:69], v[108:109], v[88:89], v[68:69] op_sel:[0,1,0] op_sel_hi:[1,1,1]
	v_pk_fma_f32 v[70:71], v[110:111], v[88:89], v[70:71] op_sel:[0,1,0] op_sel_hi:[1,1,1]
	v_cvt_pk_f32_fp8_e32 v[104:105], v18
	v_cvt_pk_f32_fp8_e32 v[108:109], v22
	v_cvt_pk_f32_fp8_sdwa v[106:107], v18 src0_sel:WORD_1
	v_cvt_pk_f32_fp8_sdwa v[110:111], v22 src0_sel:WORD_1
	v_pk_fma_f32 v[72:73], v[104:105], v[88:89], v[72:73] op_sel_hi:[1,0,1]
	v_pk_fma_f32 v[74:75], v[106:107], v[88:89], v[74:75] op_sel_hi:[1,0,1]
	v_pk_fma_f32 v[72:73], v[108:109], v[88:89], v[72:73] op_sel:[0,1,0] op_sel_hi:[1,1,1]
	v_pk_fma_f32 v[74:75], v[110:111], v[88:89], v[74:75] op_sel:[0,1,0] op_sel_hi:[1,1,1]
	v_cvt_pk_f32_fp8_e32 v[104:105], v19
	v_cvt_pk_f32_fp8_e32 v[108:109], v23
	v_cvt_pk_f32_fp8_sdwa v[106:107], v19 src0_sel:WORD_1
	v_cvt_pk_f32_fp8_sdwa v[110:111], v23 src0_sel:WORD_1
	v_pk_fma_f32 v[76:77], v[104:105], v[88:89], v[76:77] op_sel_hi:[1,0,1]
	v_pk_fma_f32 v[78:79], v[106:107], v[88:89], v[78:79] op_sel_hi:[1,0,1]
	v_and_or_b32 v138, v138, s2, v240
	v_and_or_b32 v139, v139, s2, v240
	global_load_dwordx4 v[16:19], v138, s[80:81]
	global_load_dwordx4 v[20:23], v139, s[80:81]
	v_pk_fma_f32 v[76:77], v[108:109], v[88:89], v[76:77] op_sel:[0,1,0] op_sel_hi:[1,1,1]
	v_pk_fma_f32 v[78:79], v[110:111], v[88:89], v[78:79] op_sel:[0,1,0] op_sel_hi:[1,1,1]
	s_waitcnt vmcnt(16)
	v_cvt_pk_f32_fp8_e32 v[104:105], v24
	v_cvt_pk_f32_fp8_e32 v[108:109], v28
	v_cvt_pk_f32_fp8_sdwa v[106:107], v24 src0_sel:WORD_1
	v_cvt_pk_f32_fp8_sdwa v[110:111], v28 src0_sel:WORD_1
	v_pk_fma_f32 v[64:65], v[104:105], v[90:91], v[64:65] op_sel_hi:[1,0,1]
	v_pk_fma_f32 v[66:67], v[106:107], v[90:91], v[66:67] op_sel_hi:[1,0,1]
	v_pk_fma_f32 v[64:65], v[108:109], v[90:91], v[64:65] op_sel:[0,1,0] op_sel_hi:[1,1,1]
	v_pk_fma_f32 v[66:67], v[110:111], v[90:91], v[66:67] op_sel:[0,1,0] op_sel_hi:[1,1,1]
	v_cvt_pk_f32_fp8_e32 v[104:105], v25
	v_cvt_pk_f32_fp8_e32 v[108:109], v29
	v_cvt_pk_f32_fp8_sdwa v[106:107], v25 src0_sel:WORD_1
	v_cvt_pk_f32_fp8_sdwa v[110:111], v29 src0_sel:WORD_1
	v_pk_fma_f32 v[68:69], v[104:105], v[90:91], v[68:69] op_sel_hi:[1,0,1]
	v_pk_fma_f32 v[70:71], v[106:107], v[90:91], v[70:71] op_sel_hi:[1,0,1]
	v_pk_fma_f32 v[68:69], v[108:109], v[90:91], v[68:69] op_sel:[0,1,0] op_sel_hi:[1,1,1]
	v_pk_fma_f32 v[70:71], v[110:111], v[90:91], v[70:71] op_sel:[0,1,0] op_sel_hi:[1,1,1]
	v_cvt_pk_f32_fp8_e32 v[104:105], v26
	v_cvt_pk_f32_fp8_e32 v[108:109], v30
	v_cvt_pk_f32_fp8_sdwa v[106:107], v26 src0_sel:WORD_1
	v_cvt_pk_f32_fp8_sdwa v[110:111], v30 src0_sel:WORD_1
	v_pk_fma_f32 v[72:73], v[104:105], v[90:91], v[72:73] op_sel_hi:[1,0,1]
	v_pk_fma_f32 v[74:75], v[106:107], v[90:91], v[74:75] op_sel_hi:[1,0,1]
	v_pk_fma_f32 v[72:73], v[108:109], v[90:91], v[72:73] op_sel:[0,1,0] op_sel_hi:[1,1,1]
	v_pk_fma_f32 v[74:75], v[110:111], v[90:91], v[74:75] op_sel:[0,1,0] op_sel_hi:[1,1,1]
	v_cvt_pk_f32_fp8_e32 v[104:105], v27
	v_cvt_pk_f32_fp8_e32 v[108:109], v31
	v_cvt_pk_f32_fp8_sdwa v[106:107], v27 src0_sel:WORD_1
	v_cvt_pk_f32_fp8_sdwa v[110:111], v31 src0_sel:WORD_1
	v_pk_fma_f32 v[76:77], v[104:105], v[90:91], v[76:77] op_sel_hi:[1,0,1]
	v_pk_fma_f32 v[78:79], v[106:107], v[90:91], v[78:79] op_sel_hi:[1,0,1]
	v_and_or_b32 v140, v140, s2, v240
	v_and_or_b32 v141, v141, s2, v240
	global_load_dwordx4 v[24:27], v140, s[80:81]
	global_load_dwordx4 v[28:31], v141, s[80:81]
	v_pk_fma_f32 v[76:77], v[108:109], v[90:91], v[76:77] op_sel:[0,1,0] op_sel_hi:[1,1,1]
	v_pk_fma_f32 v[78:79], v[110:111], v[90:91], v[78:79] op_sel:[0,1,0] op_sel_hi:[1,1,1]
	s_waitcnt vmcnt(16)
	v_cvt_pk_f32_fp8_e32 v[104:105], v32
	v_cvt_pk_f32_fp8_e32 v[108:109], v36
	v_cvt_pk_f32_fp8_sdwa v[106:107], v32 src0_sel:WORD_1
	v_cvt_pk_f32_fp8_sdwa v[110:111], v36 src0_sel:WORD_1
	v_pk_fma_f32 v[64:65], v[104:105], v[92:93], v[64:65] op_sel_hi:[1,0,1]
	v_pk_fma_f32 v[66:67], v[106:107], v[92:93], v[66:67] op_sel_hi:[1,0,1]
	v_pk_fma_f32 v[64:65], v[108:109], v[92:93], v[64:65] op_sel:[0,1,0] op_sel_hi:[1,1,1]
	v_pk_fma_f32 v[66:67], v[110:111], v[92:93], v[66:67] op_sel:[0,1,0] op_sel_hi:[1,1,1]
	v_cvt_pk_f32_fp8_e32 v[104:105], v33
	v_cvt_pk_f32_fp8_e32 v[108:109], v37
	v_cvt_pk_f32_fp8_sdwa v[106:107], v33 src0_sel:WORD_1
	v_cvt_pk_f32_fp8_sdwa v[110:111], v37 src0_sel:WORD_1
	v_pk_fma_f32 v[68:69], v[104:105], v[92:93], v[68:69] op_sel_hi:[1,0,1]
	v_pk_fma_f32 v[70:71], v[106:107], v[92:93], v[70:71] op_sel_hi:[1,0,1]
	v_pk_fma_f32 v[68:69], v[108:109], v[92:93], v[68:69] op_sel:[0,1,0] op_sel_hi:[1,1,1]
	v_pk_fma_f32 v[70:71], v[110:111], v[92:93], v[70:71] op_sel:[0,1,0] op_sel_hi:[1,1,1]
	v_cvt_pk_f32_fp8_e32 v[104:105], v34
	v_cvt_pk_f32_fp8_e32 v[108:109], v38
	v_cvt_pk_f32_fp8_sdwa v[106:107], v34 src0_sel:WORD_1
	v_cvt_pk_f32_fp8_sdwa v[110:111], v38 src0_sel:WORD_1
	v_pk_fma_f32 v[72:73], v[104:105], v[92:93], v[72:73] op_sel_hi:[1,0,1]
	v_pk_fma_f32 v[74:75], v[106:107], v[92:93], v[74:75] op_sel_hi:[1,0,1]
	v_pk_fma_f32 v[72:73], v[108:109], v[92:93], v[72:73] op_sel:[0,1,0] op_sel_hi:[1,1,1]
	v_pk_fma_f32 v[74:75], v[110:111], v[92:93], v[74:75] op_sel:[0,1,0] op_sel_hi:[1,1,1]
	v_cvt_pk_f32_fp8_e32 v[104:105], v35
	v_cvt_pk_f32_fp8_e32 v[108:109], v39
	v_cvt_pk_f32_fp8_sdwa v[106:107], v35 src0_sel:WORD_1
	v_cvt_pk_f32_fp8_sdwa v[110:111], v39 src0_sel:WORD_1
	v_pk_fma_f32 v[76:77], v[104:105], v[92:93], v[76:77] op_sel_hi:[1,0,1]
	v_pk_fma_f32 v[78:79], v[106:107], v[92:93], v[78:79] op_sel_hi:[1,0,1]
	v_and_or_b32 v250, v250, s2, v240
	v_and_or_b32 v251, v251, s2, v240
	global_load_dwordx4 v[32:35], v250, s[80:81]
	global_load_dwordx4 v[36:39], v251, s[80:81]
	v_pk_fma_f32 v[76:77], v[108:109], v[92:93], v[76:77] op_sel:[0,1,0] op_sel_hi:[1,1,1]
	v_pk_fma_f32 v[78:79], v[110:111], v[92:93], v[78:79] op_sel:[0,1,0] op_sel_hi:[1,1,1]
	s_waitcnt vmcnt(16)
	v_cvt_pk_f32_fp8_e32 v[104:105], v40
	v_cvt_pk_f32_fp8_e32 v[108:109], v44
	v_cvt_pk_f32_fp8_sdwa v[106:107], v40 src0_sel:WORD_1
	v_cvt_pk_f32_fp8_sdwa v[110:111], v44 src0_sel:WORD_1
	v_pk_fma_f32 v[64:65], v[104:105], v[94:95], v[64:65] op_sel_hi:[1,0,1]
	v_pk_fma_f32 v[66:67], v[106:107], v[94:95], v[66:67] op_sel_hi:[1,0,1]
	v_pk_fma_f32 v[64:65], v[108:109], v[94:95], v[64:65] op_sel:[0,1,0] op_sel_hi:[1,1,1]
	v_pk_fma_f32 v[66:67], v[110:111], v[94:95], v[66:67] op_sel:[0,1,0] op_sel_hi:[1,1,1]
	v_cvt_pk_f32_fp8_e32 v[104:105], v41
	v_cvt_pk_f32_fp8_e32 v[108:109], v45
	v_cvt_pk_f32_fp8_sdwa v[106:107], v41 src0_sel:WORD_1
	v_cvt_pk_f32_fp8_sdwa v[110:111], v45 src0_sel:WORD_1
	v_pk_fma_f32 v[68:69], v[104:105], v[94:95], v[68:69] op_sel_hi:[1,0,1]
	v_pk_fma_f32 v[70:71], v[106:107], v[94:95], v[70:71] op_sel_hi:[1,0,1]
	v_pk_fma_f32 v[68:69], v[108:109], v[94:95], v[68:69] op_sel:[0,1,0] op_sel_hi:[1,1,1]
	v_pk_fma_f32 v[70:71], v[110:111], v[94:95], v[70:71] op_sel:[0,1,0] op_sel_hi:[1,1,1]
	v_cvt_pk_f32_fp8_e32 v[104:105], v42
	v_cvt_pk_f32_fp8_e32 v[108:109], v46
	v_cvt_pk_f32_fp8_sdwa v[106:107], v42 src0_sel:WORD_1
	v_cvt_pk_f32_fp8_sdwa v[110:111], v46 src0_sel:WORD_1
	v_pk_fma_f32 v[72:73], v[104:105], v[94:95], v[72:73] op_sel_hi:[1,0,1]
	v_pk_fma_f32 v[74:75], v[106:107], v[94:95], v[74:75] op_sel_hi:[1,0,1]
	v_pk_fma_f32 v[72:73], v[108:109], v[94:95], v[72:73] op_sel:[0,1,0] op_sel_hi:[1,1,1]
	v_pk_fma_f32 v[74:75], v[110:111], v[94:95], v[74:75] op_sel:[0,1,0] op_sel_hi:[1,1,1]
	v_cvt_pk_f32_fp8_e32 v[104:105], v43
	v_cvt_pk_f32_fp8_e32 v[108:109], v47
	v_cvt_pk_f32_fp8_sdwa v[106:107], v43 src0_sel:WORD_1
	v_cvt_pk_f32_fp8_sdwa v[110:111], v47 src0_sel:WORD_1
	v_pk_fma_f32 v[76:77], v[104:105], v[94:95], v[76:77] op_sel_hi:[1,0,1]
	v_pk_fma_f32 v[78:79], v[106:107], v[94:95], v[78:79] op_sel_hi:[1,0,1]
	v_and_or_b32 v252, v252, s2, v240
	v_and_or_b32 v253, v253, s2, v240
	global_load_dwordx4 v[40:43], v252, s[80:81]
	global_load_dwordx4 v[44:47], v253, s[80:81]
	v_pk_fma_f32 v[76:77], v[108:109], v[94:95], v[76:77] op_sel:[0,1,0] op_sel_hi:[1,1,1]
	v_pk_fma_f32 v[78:79], v[110:111], v[94:95], v[78:79] op_sel:[0,1,0] op_sel_hi:[1,1,1]
	s_waitcnt vmcnt(16)
	v_cvt_pk_f32_fp8_e32 v[104:105], v48
	v_cvt_pk_f32_fp8_e32 v[108:109], v52
	v_cvt_pk_f32_fp8_sdwa v[106:107], v48 src0_sel:WORD_1
	v_cvt_pk_f32_fp8_sdwa v[110:111], v52 src0_sel:WORD_1
	v_pk_fma_f32 v[64:65], v[104:105], v[96:97], v[64:65] op_sel_hi:[1,0,1]
	v_pk_fma_f32 v[66:67], v[106:107], v[96:97], v[66:67] op_sel_hi:[1,0,1]
	v_pk_fma_f32 v[64:65], v[108:109], v[96:97], v[64:65] op_sel:[0,1,0] op_sel_hi:[1,1,1]
	v_pk_fma_f32 v[66:67], v[110:111], v[96:97], v[66:67] op_sel:[0,1,0] op_sel_hi:[1,1,1]
	v_cvt_pk_f32_fp8_e32 v[104:105], v49
	v_cvt_pk_f32_fp8_e32 v[108:109], v53
	v_cvt_pk_f32_fp8_sdwa v[106:107], v49 src0_sel:WORD_1
	v_cvt_pk_f32_fp8_sdwa v[110:111], v53 src0_sel:WORD_1
	v_pk_fma_f32 v[68:69], v[104:105], v[96:97], v[68:69] op_sel_hi:[1,0,1]
	v_pk_fma_f32 v[70:71], v[106:107], v[96:97], v[70:71] op_sel_hi:[1,0,1]
	v_pk_fma_f32 v[68:69], v[108:109], v[96:97], v[68:69] op_sel:[0,1,0] op_sel_hi:[1,1,1]
	v_pk_fma_f32 v[70:71], v[110:111], v[96:97], v[70:71] op_sel:[0,1,0] op_sel_hi:[1,1,1]
	v_cvt_pk_f32_fp8_e32 v[104:105], v50
	v_cvt_pk_f32_fp8_e32 v[108:109], v54
	v_cvt_pk_f32_fp8_sdwa v[106:107], v50 src0_sel:WORD_1
	v_cvt_pk_f32_fp8_sdwa v[110:111], v54 src0_sel:WORD_1
	v_pk_fma_f32 v[72:73], v[104:105], v[96:97], v[72:73] op_sel_hi:[1,0,1]
	v_pk_fma_f32 v[74:75], v[106:107], v[96:97], v[74:75] op_sel_hi:[1,0,1]
	v_pk_fma_f32 v[72:73], v[108:109], v[96:97], v[72:73] op_sel:[0,1,0] op_sel_hi:[1,1,1]
	v_pk_fma_f32 v[74:75], v[110:111], v[96:97], v[74:75] op_sel:[0,1,0] op_sel_hi:[1,1,1]
	v_cvt_pk_f32_fp8_e32 v[104:105], v51
	v_cvt_pk_f32_fp8_e32 v[108:109], v55
	v_cvt_pk_f32_fp8_sdwa v[106:107], v51 src0_sel:WORD_1
	v_cvt_pk_f32_fp8_sdwa v[110:111], v55 src0_sel:WORD_1
	v_pk_fma_f32 v[76:77], v[104:105], v[96:97], v[76:77] op_sel_hi:[1,0,1]
	v_pk_fma_f32 v[78:79], v[106:107], v[96:97], v[78:79] op_sel_hi:[1,0,1]
	v_and_or_b32 v242, v242, s2, v240
	v_and_or_b32 v243, v243, s2, v240
	global_load_dwordx4 v[48:51], v242, s[80:81]
	global_load_dwordx4 v[52:55], v243, s[80:81]
	v_pk_fma_f32 v[76:77], v[108:109], v[96:97], v[76:77] op_sel:[0,1,0] op_sel_hi:[1,1,1]
	v_pk_fma_f32 v[78:79], v[110:111], v[96:97], v[78:79] op_sel:[0,1,0] op_sel_hi:[1,1,1]
	s_waitcnt vmcnt(16)
; #define PG_ISSUE(BUF, TAB, e0_) do { const int isrc_ = ((e0_) < 64) ? myi0 : myi1; \
;       _Pragma("unroll") for (int e = 0; e < 8; ++e) { const int idx_ = __builtin_amdgcn_readlane(isrc_, ((e0_) + e) & 63); \
;         BUF[e] = *(const u32x4*)((TAB) + (size_t)idx_ * 1024 + lane * 16); } } while (0)
; DEV void peer_gather(const Params& P, int l, int m0, const int* idxs, const float* gs) {
;     ...
;     PG_ISSUE(b0, U, 0);
; #pragma nounroll
;     for (int e0 = 0; e0 < 128; e0 += 16) {
;       PG_ISSUE(b1, U, e0 + 8);
;       PG_U8(b0, 0, e0);
;       if (e0 + 16 < 128) PG_ISSUE(b0, U, e0 + 16); else PG_ISSUE(b0, V, 0);
;       PG_U8(b1, 0, e0 + 8);
;     }
;     float* hrow = P.out + tok * DM + lane * 16;
;     f32x4 hv[4];
; #pragma unroll
;     for (int q = 0; q < 4; ++q) hv[q] = *(const f32x4*)(hrow + 4 * q);
;     if (i + 1 < 16) {
;       const int tn = tt + 1;
;       nxa = *(const u32x4*)(hn + (size_t)(m0 + tn) * DM + lane * 16); nxb = *(const u32x4*)(hn + (size_t)(m0 + tn) * DM + lane * 16 + 8);
;       ni0 = idxs[tn * 128 + lane]; ni1 = idxs[tn * 128 + 64 + lane]; ng0 = gs[tn * 128 + lane]; ng1 = gs[tn * 128 + 64 + lane];
;     }
; #pragma nounroll
;     for (int e0 = 0; e0 < 128; e0 += 16) {
;       PG_ISSUE(b1, V, e0 + 8);
;       if (e0 == 64 && i + 1 < 16) sort_lists(lane, ni0, ni1, ng0, ng1);
;       PG_V16(b0, e0);
;       if (e0 + 16 < 128) PG_ISSUE(b0, V, e0 + 16);
;       PG_V16(b1, e0 + 8);
;     }
	v_cvt_pk_f32_fp8_e32 v[104:105], v56
	v_cvt_pk_f32_fp8_e32 v[108:109], v60
	v_cvt_pk_f32_fp8_sdwa v[106:107], v56 src0_sel:WORD_1
	v_cvt_pk_f32_fp8_sdwa v[110:111], v60 src0_sel:WORD_1
	v_pk_fma_f32 v[64:65], v[104:105], v[98:99], v[64:65] op_sel_hi:[1,0,1]
	v_pk_fma_f32 v[66:67], v[106:107], v[98:99], v[66:67] op_sel_hi:[1,0,1]
	v_pk_fma_f32 v[64:65], v[108:109], v[98:99], v[64:65] op_sel:[0,1,0] op_sel_hi:[1,1,1]
	v_pk_fma_f32 v[66:67], v[110:111], v[98:99], v[66:67] op_sel:[0,1,0] op_sel_hi:[1,1,1]
	v_cvt_pk_f32_fp8_e32 v[104:105], v57
	v_cvt_pk_f32_fp8_e32 v[108:109], v61
	v_cvt_pk_f32_fp8_sdwa v[106:107], v57 src0_sel:WORD_1
	v_cvt_pk_f32_fp8_sdwa v[110:111], v61 src0_sel:WORD_1
	v_pk_fma_f32 v[68:69], v[104:105], v[98:99], v[68:69] op_sel_hi:[1,0,1]
	v_pk_fma_f32 v[70:71], v[106:107], v[98:99], v[70:71] op_sel_hi:[1,0,1]
	v_pk_fma_f32 v[68:69], v[108:109], v[98:99], v[68:69] op_sel:[0,1,0] op_sel_hi:[1,1,1]
	v_pk_fma_f32 v[70:71], v[110:111], v[98:99], v[70:71] op_sel:[0,1,0] op_sel_hi:[1,1,1]
	v_cvt_pk_f32_fp8_e32 v[104:105], v58
	v_cvt_pk_f32_fp8_e32 v[108:109], v62
	v_cvt_pk_f32_fp8_sdwa v[106:107], v58 src0_sel:WORD_1
	v_cvt_pk_f32_fp8_sdwa v[110:111], v62 src0_sel:WORD_1
	v_pk_fma_f32 v[72:73], v[104:105], v[98:99], v[72:73] op_sel_hi:[1,0,1]
	v_pk_fma_f32 v[74:75], v[106:107], v[98:99], v[74:75] op_sel_hi:[1,0,1]
	v_pk_fma_f32 v[72:73], v[108:109], v[98:99], v[72:73] op_sel:[0,1,0] op_sel_hi:[1,1,1]
	v_pk_fma_f32 v[74:75], v[110:111], v[98:99], v[74:75] op_sel:[0,1,0] op_sel_hi:[1,1,1]
	v_cvt_pk_f32_fp8_e32 v[104:105], v59
	v_cvt_pk_f32_fp8_e32 v[108:109], v63
	v_cvt_pk_f32_fp8_sdwa v[106:107], v59 src0_sel:WORD_1
	v_cvt_pk_f32_fp8_sdwa v[110:111], v63 src0_sel:WORD_1
	v_pk_fma_f32 v[76:77], v[104:105], v[98:99], v[76:77] op_sel_hi:[1,0,1]
	v_pk_fma_f32 v[78:79], v[106:107], v[98:99], v[78:79] op_sel_hi:[1,0,1]
	v_and_or_b32 v244, v244, s2, v240
	v_and_or_b32 v245, v245, s2, v240
	global_load_dwordx4 v[56:59], v244, s[80:81]
	global_load_dwordx4 v[60:63], v245, s[80:81]
	v_pk_fma_f32 v[76:77], v[108:109], v[98:99], v[76:77] op_sel:[0,1,0] op_sel_hi:[1,1,1]
	v_pk_fma_f32 v[78:79], v[110:111], v[98:99], v[78:79] op_sel:[0,1,0] op_sel_hi:[1,1,1]
	s_add_u32 s92, s100, 2
	s_and_b32 s92, s92, 15
	v_lshl_add_u32 v116, s92, 9, v246
	ds_read_b128 v[112:115], v116
	ds_read_b128 v[138:141], v116 offset:16
	ds_read_b128 v[250:253], v116 offset:32
	ds_read_b128 v[242:245], v116 offset:48
	s_add_u32 s92, s100, 1
	s_and_b32 s92, s92, 15
	v_lshl_add_u32 v117, s92, 9, v247
	ds_read_b128 v[84:87], v117
	ds_read_b128 v[88:91], v117 offset:16
	ds_read_b128 v[92:95], v117 offset:32
	ds_read_b128 v[96:99], v117 offset:48
	s_nop 1
	v_permlane32_swap_b32_e32 v64, v66
	v_permlane32_swap_b32_e32 v65, v67
	v_permlane32_swap_b32_e32 v68, v70
	v_permlane32_swap_b32_e32 v69, v71
	v_permlane32_swap_b32_e32 v72, v74
	v_permlane32_swap_b32_e32 v73, v75
	v_permlane32_swap_b32_e32 v76, v78
	v_permlane32_swap_b32_e32 v77, v79
	v_add_f32_e32 v64, v64, v66
	v_add_f32_e32 v65, v65, v67
	v_add_f32_e32 v68, v68, v70
	v_add_f32_e32 v69, v69, v71
	v_add_f32_e32 v72, v72, v74
	v_add_f32_e32 v73, v73, v75
	v_add_f32_e32 v76, v76, v78
	v_add_f32_e32 v77, v77, v79
	s_nop 1
	v_permlane16_swap_b32_e32 v64, v68
	v_permlane16_swap_b32_e32 v65, v69
	v_permlane16_swap_b32_e32 v72, v76
	v_permlane16_swap_b32_e32 v73, v77
	v_add_f32_e32 v64, v64, v68
	v_add_f32_e32 v65, v65, v69
	v_add_f32_e32 v72, v72, v76
	v_add_f32_e32 v73, v73, v77
	s_nop 0
	v_cndmask_b32_e64 v66, v64, v72, s[88:89]
	v_cndmask_b32_e64 v67, v72, v64, s[88:89]
	v_cndmask_b32_e64 v74, v65, v73, s[88:89]
	v_cndmask_b32_e64 v75, v73, v65, s[88:89]
	s_nop 1
	v_add_f32_dpp v64, v67, v66 row_ror:8 row_mask:0xf bank_mask:0xf
	v_add_f32_dpp v65, v75, v74 row_ror:8 row_mask:0xf bank_mask:0xf
	v_fmac_f32_e32 v80, 0x3c800000, v64
	v_fmac_f32_e32 v81, 0x3c800000, v65
	global_store_dwordx2 v119, v[80:81], s[82:83]
	s_add_u32 s100, s100, 1
	s_barrier
	s_add_u32 s98, s100, 1
	s_min_u32 s98, s98, 127
	s_lshr_b32 s93, s98, 4
	s_and_b32 s98, s98, 15
	s_lshl3_add_u32 vcc_lo, s98, s93
	v_lshl_add_u32 v119, vcc_lo, 9, v238
	global_load_dwordx2 v[80:81], v119, s[82:83]
	v_lshl_or_b32 v240, s93, 21, v235
	s_waitcnt lgkmcnt(0)
	s_waitcnt vmcnt(16)
	v_cvt_pk_f32_fp8_e32 v[104:105], v0
	v_cvt_pk_f32_fp8_e32 v[108:109], v4
	v_cvt_pk_f32_fp8_sdwa v[106:107], v0 src0_sel:WORD_1
	v_cvt_pk_f32_fp8_sdwa v[110:111], v4 src0_sel:WORD_1
	v_pk_mul_f32 v[64:65], v[104:105], v[84:85] op_sel_hi:[1,0]
	v_pk_mul_f32 v[66:67], v[106:107], v[84:85] op_sel_hi:[1,0]
	v_pk_fma_f32 v[64:65], v[108:109], v[84:85], v[64:65] op_sel:[0,1,0] op_sel_hi:[1,1,1]
	v_pk_fma_f32 v[66:67], v[110:111], v[84:85], v[66:67] op_sel:[0,1,0] op_sel_hi:[1,1,1]
	v_cvt_pk_f32_fp8_e32 v[104:105], v1
	v_cvt_pk_f32_fp8_e32 v[108:109], v5
	v_cvt_pk_f32_fp8_sdwa v[106:107], v1 src0_sel:WORD_1
	v_cvt_pk_f32_fp8_sdwa v[110:111], v5 src0_sel:WORD_1
	v_pk_mul_f32 v[68:69], v[104:105], v[84:85] op_sel_hi:[1,0]
	v_pk_mul_f32 v[70:71], v[106:107], v[84:85] op_sel_hi:[1,0]
	v_pk_fma_f32 v[68:69], v[108:109], v[84:85], v[68:69] op_sel:[0,1,0] op_sel_hi:[1,1,1]
	v_pk_fma_f32 v[70:71], v[110:111], v[84:85], v[70:71] op_sel:[0,1,0] op_sel_hi:[1,1,1]
	v_cvt_pk_f32_fp8_e32 v[104:105], v2
	v_cvt_pk_f32_fp8_e32 v[108:109], v6
	v_cvt_pk_f32_fp8_sdwa v[106:107], v2 src0_sel:WORD_1
	v_cvt_pk_f32_fp8_sdwa v[110:111], v6 src0_sel:WORD_1
	v_pk_mul_f32 v[72:73], v[104:105], v[84:85] op_sel_hi:[1,0]
	v_pk_mul_f32 v[74:75], v[106:107], v[84:85] op_sel_hi:[1,0]
	v_pk_fma_f32 v[72:73], v[108:109], v[84:85], v[72:73] op_sel:[0,1,0] op_sel_hi:[1,1,1]
	v_pk_fma_f32 v[74:75], v[110:111], v[84:85], v[74:75] op_sel:[0,1,0] op_sel_hi:[1,1,1]
	v_cvt_pk_f32_fp8_e32 v[104:105], v3
	v_cvt_pk_f32_fp8_e32 v[108:109], v7
	v_cvt_pk_f32_fp8_sdwa v[106:107], v3 src0_sel:WORD_1
	v_cvt_pk_f32_fp8_sdwa v[110:111], v7 src0_sel:WORD_1
	v_pk_mul_f32 v[76:77], v[104:105], v[84:85] op_sel_hi:[1,0]
	v_pk_mul_f32 v[78:79], v[106:107], v[84:85] op_sel_hi:[1,0]
	v_and_or_b32 v112, v112, s2, v240
	v_and_or_b32 v113, v113, s2, v240
	global_load_dwordx4 v[0:3], v112, s[80:81]
	global_load_dwordx4 v[4:7], v113, s[80:81]
	v_pk_fma_f32 v[76:77], v[108:109], v[84:85], v[76:77] op_sel:[0,1,0] op_sel_hi:[1,1,1]
	v_pk_fma_f32 v[78:79], v[110:111], v[84:85], v[78:79] op_sel:[0,1,0] op_sel_hi:[1,1,1]
	s_waitcnt vmcnt(16)
	v_cvt_pk_f32_fp8_e32 v[104:105], v8
	v_cvt_pk_f32_fp8_e32 v[108:109], v12
	v_cvt_pk_f32_fp8_sdwa v[106:107], v8 src0_sel:WORD_1
	v_cvt_pk_f32_fp8_sdwa v[110:111], v12 src0_sel:WORD_1
	v_pk_fma_f32 v[64:65], v[104:105], v[86:87], v[64:65] op_sel_hi:[1,0,1]
	v_pk_fma_f32 v[66:67], v[106:107], v[86:87], v[66:67] op_sel_hi:[1,0,1]
	v_pk_fma_f32 v[64:65], v[108:109], v[86:87], v[64:65] op_sel:[0,1,0] op_sel_hi:[1,1,1]
	v_pk_fma_f32 v[66:67], v[110:111], v[86:87], v[66:67] op_sel:[0,1,0] op_sel_hi:[1,1,1]
	v_cvt_pk_f32_fp8_e32 v[104:105], v9
	v_cvt_pk_f32_fp8_e32 v[108:109], v13
	v_cvt_pk_f32_fp8_sdwa v[106:107], v9 src0_sel:WORD_1
	v_cvt_pk_f32_fp8_sdwa v[110:111], v13 src0_sel:WORD_1
	v_pk_fma_f32 v[68:69], v[104:105], v[86:87], v[68:69] op_sel_hi:[1,0,1]
	v_pk_fma_f32 v[70:71], v[106:107], v[86:87], v[70:71] op_sel_hi:[1,0,1]
	v_pk_fma_f32 v[68:69], v[108:109], v[86:87], v[68:69] op_sel:[0,1,0] op_sel_hi:[1,1,1]
	v_pk_fma_f32 v[70:71], v[110:111], v[86:87], v[70:71] op_sel:[0,1,0] op_sel_hi:[1,1,1]
	v_cvt_pk_f32_fp8_e32 v[104:105], v10
	v_cvt_pk_f32_fp8_e32 v[108:109], v14
	v_cvt_pk_f32_fp8_sdwa v[106:107], v10 src0_sel:WORD_1
	v_cvt_pk_f32_fp8_sdwa v[110:111], v14 src0_sel:WORD_1
	v_pk_fma_f32 v[72:73], v[104:105], v[86:87], v[72:73] op_sel_hi:[1,0,1]
	v_pk_fma_f32 v[74:75], v[106:107], v[86:87], v[74:75] op_sel_hi:[1,0,1]
	v_pk_fma_f32 v[72:73], v[108:109], v[86:87], v[72:73] op_sel:[0,1,0] op_sel_hi:[1,1,1]
	v_pk_fma_f32 v[74:75], v[110:111], v[86:87], v[74:75] op_sel:[0,1,0] op_sel_hi:[1,1,1]
	v_cvt_pk_f32_fp8_e32 v[104:105], v11
	v_cvt_pk_f32_fp8_e32 v[108:109], v15
	v_cvt_pk_f32_fp8_sdwa v[106:107], v11 src0_sel:WORD_1
	v_cvt_pk_f32_fp8_sdwa v[110:111], v15 src0_sel:WORD_1
	v_pk_fma_f32 v[76:77], v[104:105], v[86:87], v[76:77] op_sel_hi:[1,0,1]
	v_pk_fma_f32 v[78:79], v[106:107], v[86:87], v[78:79] op_sel_hi:[1,0,1]
	v_and_or_b32 v114, v114, s2, v240
	v_and_or_b32 v115, v115, s2, v240
	global_load_dwordx4 v[8:11], v114, s[80:81]
	global_load_dwordx4 v[12:15], v115, s[80:81]
	v_pk_fma_f32 v[76:77], v[108:109], v[86:87], v[76:77] op_sel:[0,1,0] op_sel_hi:[1,1,1]
	v_pk_fma_f32 v[78:79], v[110:111], v[86:87], v[78:79] op_sel:[0,1,0] op_sel_hi:[1,1,1]
	s_waitcnt vmcnt(16)
	v_cvt_pk_f32_fp8_e32 v[104:105], v16
	v_cvt_pk_f32_fp8_e32 v[108:109], v20
	v_cvt_pk_f32_fp8_sdwa v[106:107], v16 src0_sel:WORD_1
	v_cvt_pk_f32_fp8_sdwa v[110:111], v20 src0_sel:WORD_1
	v_pk_fma_f32 v[64:65], v[104:105], v[88:89], v[64:65] op_sel_hi:[1,0,1]
	v_pk_fma_f32 v[66:67], v[106:107], v[88:89], v[66:67] op_sel_hi:[1,0,1]
	v_pk_fma_f32 v[64:65], v[108:109], v[88:89], v[64:65] op_sel:[0,1,0] op_sel_hi:[1,1,1]
	v_pk_fma_f32 v[66:67], v[110:111], v[88:89], v[66:67] op_sel:[0,1,0] op_sel_hi:[1,1,1]
	v_cvt_pk_f32_fp8_e32 v[104:105], v17
	v_cvt_pk_f32_fp8_e32 v[108:109], v21
	v_cvt_pk_f32_fp8_sdwa v[106:107], v17 src0_sel:WORD_1
	v_cvt_pk_f32_fp8_sdwa v[110:111], v21 src0_sel:WORD_1
	v_pk_fma_f32 v[68:69], v[104:105], v[88:89], v[68:69] op_sel_hi:[1,0,1]
	v_pk_fma_f32 v[70:71], v[106:107], v[88:89], v[70:71] op_sel_hi:[1,0,1]
	v_pk_fma_f32 v[68:69], v[108:109], v[88:89], v[68:69] op_sel:[0,1,0] op_sel_hi:[1,1,1]
	v_pk_fma_f32 v[70:71], v[110:111], v[88:89], v[70:71] op_sel:[0,1,0] op_sel_hi:[1,1,1]
	v_cvt_pk_f32_fp8_e32 v[104:105], v18
	v_cvt_pk_f32_fp8_e32 v[108:109], v22
	v_cvt_pk_f32_fp8_sdwa v[106:107], v18 src0_sel:WORD_1
	v_cvt_pk_f32_fp8_sdwa v[110:111], v22 src0_sel:WORD_1
	v_pk_fma_f32 v[72:73], v[104:105], v[88:89], v[72:73] op_sel_hi:[1,0,1]
	v_pk_fma_f32 v[74:75], v[106:107], v[88:89], v[74:75] op_sel_hi:[1,0,1]
	v_pk_fma_f32 v[72:73], v[108:109], v[88:89], v[72:73] op_sel:[0,1,0] op_sel_hi:[1,1,1]
	v_pk_fma_f32 v[74:75], v[110:111], v[88:89], v[74:75] op_sel:[0,1,0] op_sel_hi:[1,1,1]
	v_cvt_pk_f32_fp8_e32 v[104:105], v19
	v_cvt_pk_f32_fp8_e32 v[108:109], v23
	v_cvt_pk_f32_fp8_sdwa v[106:107], v19 src0_sel:WORD_1
	v_cvt_pk_f32_fp8_sdwa v[110:111], v23 src0_sel:WORD_1
	v_pk_fma_f32 v[76:77], v[104:105], v[88:89], v[76:77] op_sel_hi:[1,0,1]
	v_pk_fma_f32 v[78:79], v[106:107], v[88:89], v[78:79] op_sel_hi:[1,0,1]
	v_and_or_b32 v138, v138, s2, v240
	v_and_or_b32 v139, v139, s2, v240
	global_load_dwordx4 v[16:19], v138, s[80:81]
	global_load_dwordx4 v[20:23], v139, s[80:81]
	v_pk_fma_f32 v[76:77], v[108:109], v[88:89], v[76:77] op_sel:[0,1,0] op_sel_hi:[1,1,1]
	v_pk_fma_f32 v[78:79], v[110:111], v[88:89], v[78:79] op_sel:[0,1,0] op_sel_hi:[1,1,1]
	s_waitcnt vmcnt(16)
	v_cvt_pk_f32_fp8_e32 v[104:105], v24
	v_cvt_pk_f32_fp8_e32 v[108:109], v28
	v_cvt_pk_f32_fp8_sdwa v[106:107], v24 src0_sel:WORD_1
	v_cvt_pk_f32_fp8_sdwa v[110:111], v28 src0_sel:WORD_1
	v_pk_fma_f32 v[64:65], v[104:105], v[90:91], v[64:65] op_sel_hi:[1,0,1]
	v_pk_fma_f32 v[66:67], v[106:107], v[90:91], v[66:67] op_sel_hi:[1,0,1]
	v_pk_fma_f32 v[64:65], v[108:109], v[90:91], v[64:65] op_sel:[0,1,0] op_sel_hi:[1,1,1]
	v_pk_fma_f32 v[66:67], v[110:111], v[90:91], v[66:67] op_sel:[0,1,0] op_sel_hi:[1,1,1]
	v_cvt_pk_f32_fp8_e32 v[104:105], v25
	v_cvt_pk_f32_fp8_e32 v[108:109], v29
	v_cvt_pk_f32_fp8_sdwa v[106:107], v25 src0_sel:WORD_1
	v_cvt_pk_f32_fp8_sdwa v[110:111], v29 src0_sel:WORD_1
	v_pk_fma_f32 v[68:69], v[104:105], v[90:91], v[68:69] op_sel_hi:[1,0,1]
	v_pk_fma_f32 v[70:71], v[106:107], v[90:91], v[70:71] op_sel_hi:[1,0,1]
	v_pk_fma_f32 v[68:69], v[108:109], v[90:91], v[68:69] op_sel:[0,1,0] op_sel_hi:[1,1,1]
	v_pk_fma_f32 v[70:71], v[110:111], v[90:91], v[70:71] op_sel:[0,1,0] op_sel_hi:[1,1,1]
	v_cvt_pk_f32_fp8_e32 v[104:105], v26
	v_cvt_pk_f32_fp8_e32 v[108:109], v30
	v_cvt_pk_f32_fp8_sdwa v[106:107], v26 src0_sel:WORD_1
	v_cvt_pk_f32_fp8_sdwa v[110:111], v30 src0_sel:WORD_1
	v_pk_fma_f32 v[72:73], v[104:105], v[90:91], v[72:73] op_sel_hi:[1,0,1]
	v_pk_fma_f32 v[74:75], v[106:107], v[90:91], v[74:75] op_sel_hi:[1,0,1]
	v_pk_fma_f32 v[72:73], v[108:109], v[90:91], v[72:73] op_sel:[0,1,0] op_sel_hi:[1,1,1]
	v_pk_fma_f32 v[74:75], v[110:111], v[90:91], v[74:75] op_sel:[0,1,0] op_sel_hi:[1,1,1]
	v_cvt_pk_f32_fp8_e32 v[104:105], v27
	v_cvt_pk_f32_fp8_e32 v[108:109], v31
	v_cvt_pk_f32_fp8_sdwa v[106:107], v27 src0_sel:WORD_1
	v_cvt_pk_f32_fp8_sdwa v[110:111], v31 src0_sel:WORD_1
	v_pk_fma_f32 v[76:77], v[104:105], v[90:91], v[76:77] op_sel_hi:[1,0,1]
	v_pk_fma_f32 v[78:79], v[106:107], v[90:91], v[78:79] op_sel_hi:[1,0,1]
	v_and_or_b32 v140, v140, s2, v240
	v_and_or_b32 v141, v141, s2, v240
	global_load_dwordx4 v[24:27], v140, s[80:81]
	global_load_dwordx4 v[28:31], v141, s[80:81]
	v_pk_fma_f32 v[76:77], v[108:109], v[90:91], v[76:77] op_sel:[0,1,0] op_sel_hi:[1,1,1]
	v_pk_fma_f32 v[78:79], v[110:111], v[90:91], v[78:79] op_sel:[0,1,0] op_sel_hi:[1,1,1]
	s_waitcnt vmcnt(16)
	v_cvt_pk_f32_fp8_e32 v[104:105], v32
	v_cvt_pk_f32_fp8_e32 v[108:109], v36
	v_cvt_pk_f32_fp8_sdwa v[106:107], v32 src0_sel:WORD_1
	v_cvt_pk_f32_fp8_sdwa v[110:111], v36 src0_sel:WORD_1
	v_pk_fma_f32 v[64:65], v[104:105], v[92:93], v[64:65] op_sel_hi:[1,0,1]
	v_pk_fma_f32 v[66:67], v[106:107], v[92:93], v[66:67] op_sel_hi:[1,0,1]
	v_pk_fma_f32 v[64:65], v[108:109], v[92:93], v[64:65] op_sel:[0,1,0] op_sel_hi:[1,1,1]
	v_pk_fma_f32 v[66:67], v[110:111], v[92:93], v[66:67] op_sel:[0,1,0] op_sel_hi:[1,1,1]
	v_cvt_pk_f32_fp8_e32 v[104:105], v33
	v_cvt_pk_f32_fp8_e32 v[108:109], v37
	v_cvt_pk_f32_fp8_sdwa v[106:107], v33 src0_sel:WORD_1
	v_cvt_pk_f32_fp8_sdwa v[110:111], v37 src0_sel:WORD_1
	v_pk_fma_f32 v[68:69], v[104:105], v[92:93], v[68:69] op_sel_hi:[1,0,1]
	v_pk_fma_f32 v[70:71], v[106:107], v[92:93], v[70:71] op_sel_hi:[1,0,1]
	v_pk_fma_f32 v[68:69], v[108:109], v[92:93], v[68:69] op_sel:[0,1,0] op_sel_hi:[1,1,1]
	v_pk_fma_f32 v[70:71], v[110:111], v[92:93], v[70:71] op_sel:[0,1,0] op_sel_hi:[1,1,1]
	v_cvt_pk_f32_fp8_e32 v[104:105], v34
	v_cvt_pk_f32_fp8_e32 v[108:109], v38
	v_cvt_pk_f32_fp8_sdwa v[106:107], v34 src0_sel:WORD_1
	v_cvt_pk_f32_fp8_sdwa v[110:111], v38 src0_sel:WORD_1
	v_pk_fma_f32 v[72:73], v[104:105], v[92:93], v[72:73] op_sel_hi:[1,0,1]
	v_pk_fma_f32 v[74:75], v[106:107], v[92:93], v[74:75] op_sel_hi:[1,0,1]
	v_pk_fma_f32 v[72:73], v[108:109], v[92:93], v[72:73] op_sel:[0,1,0] op_sel_hi:[1,1,1]
	v_pk_fma_f32 v[74:75], v[110:111], v[92:93], v[74:75] op_sel:[0,1,0] op_sel_hi:[1,1,1]
	v_cvt_pk_f32_fp8_e32 v[104:105], v35
	v_cvt_pk_f32_fp8_e32 v[108:109], v39
	v_cvt_pk_f32_fp8_sdwa v[106:107], v35 src0_sel:WORD_1
	v_cvt_pk_f32_fp8_sdwa v[110:111], v39 src0_sel:WORD_1
	v_pk_fma_f32 v[76:77], v[104:105], v[92:93], v[76:77] op_sel_hi:[1,0,1]
	v_pk_fma_f32 v[78:79], v[106:107], v[92:93], v[78:79] op_sel_hi:[1,0,1]
	v_and_or_b32 v250, v250, s2, v240
	v_and_or_b32 v251, v251, s2, v240
	global_load_dwordx4 v[32:35], v250, s[80:81]
	global_load_dwordx4 v[36:39], v251, s[80:81]
	v_pk_fma_f32 v[76:77], v[108:109], v[92:93], v[76:77] op_sel:[0,1,0] op_sel_hi:[1,1,1]
	v_pk_fma_f32 v[78:79], v[110:111], v[92:93], v[78:79] op_sel:[0,1,0] op_sel_hi:[1,1,1]
	s_waitcnt vmcnt(16)
	v_cvt_pk_f32_fp8_e32 v[104:105], v40
	v_cvt_pk_f32_fp8_e32 v[108:109], v44
	v_cvt_pk_f32_fp8_sdwa v[106:107], v40 src0_sel:WORD_1
	v_cvt_pk_f32_fp8_sdwa v[110:111], v44 src0_sel:WORD_1
	v_pk_fma_f32 v[64:65], v[104:105], v[94:95], v[64:65] op_sel_hi:[1,0,1]
	v_pk_fma_f32 v[66:67], v[106:107], v[94:95], v[66:67] op_sel_hi:[1,0,1]
	v_pk_fma_f32 v[64:65], v[108:109], v[94:95], v[64:65] op_sel:[0,1,0] op_sel_hi:[1,1,1]
	v_pk_fma_f32 v[66:67], v[110:111], v[94:95], v[66:67] op_sel:[0,1,0] op_sel_hi:[1,1,1]
	v_cvt_pk_f32_fp8_e32 v[104:105], v41
	v_cvt_pk_f32_fp8_e32 v[108:109], v45
	v_cvt_pk_f32_fp8_sdwa v[106:107], v41 src0_sel:WORD_1
	v_cvt_pk_f32_fp8_sdwa v[110:111], v45 src0_sel:WORD_1
	v_pk_fma_f32 v[68:69], v[104:105], v[94:95], v[68:69] op_sel_hi:[1,0,1]
	v_pk_fma_f32 v[70:71], v[106:107], v[94:95], v[70:71] op_sel_hi:[1,0,1]
	v_pk_fma_f32 v[68:69], v[108:109], v[94:95], v[68:69] op_sel:[0,1,0] op_sel_hi:[1,1,1]
	v_pk_fma_f32 v[70:71], v[110:111], v[94:95], v[70:71] op_sel:[0,1,0] op_sel_hi:[1,1,1]
	v_cvt_pk_f32_fp8_e32 v[104:105], v42
	v_cvt_pk_f32_fp8_e32 v[108:109], v46
	v_cvt_pk_f32_fp8_sdwa v[106:107], v42 src0_sel:WORD_1
	v_cvt_pk_f32_fp8_sdwa v[110:111], v46 src0_sel:WORD_1
	v_pk_fma_f32 v[72:73], v[104:105], v[94:95], v[72:73] op_sel_hi:[1,0,1]
	v_pk_fma_f32 v[74:75], v[106:107], v[94:95], v[74:75] op_sel_hi:[1,0,1]
	v_pk_fma_f32 v[72:73], v[108:109], v[94:95], v[72:73] op_sel:[0,1,0] op_sel_hi:[1,1,1]
	v_pk_fma_f32 v[74:75], v[110:111], v[94:95], v[74:75] op_sel:[0,1,0] op_sel_hi:[1,1,1]
	v_cvt_pk_f32_fp8_e32 v[104:105], v43
	v_cvt_pk_f32_fp8_e32 v[108:109], v47
	v_cvt_pk_f32_fp8_sdwa v[106:107], v43 src0_sel:WORD_1
	v_cvt_pk_f32_fp8_sdwa v[110:111], v47 src0_sel:WORD_1
	v_pk_fma_f32 v[76:77], v[104:105], v[94:95], v[76:77] op_sel_hi:[1,0,1]
	v_pk_fma_f32 v[78:79], v[106:107], v[94:95], v[78:79] op_sel_hi:[1,0,1]
	v_and_or_b32 v252, v252, s2, v240
	v_and_or_b32 v253, v253, s2, v240
	global_load_dwordx4 v[40:43], v252, s[80:81]
	global_load_dwordx4 v[44:47], v253, s[80:81]
	v_pk_fma_f32 v[76:77], v[108:109], v[94:95], v[76:77] op_sel:[0,1,0] op_sel_hi:[1,1,1]
	v_pk_fma_f32 v[78:79], v[110:111], v[94:95], v[78:79] op_sel:[0,1,0] op_sel_hi:[1,1,1]
	s_waitcnt vmcnt(16)
; #define PG_ISSUE(BUF, TAB, e0_) do { const int isrc_ = ((e0_) < 64) ? myi0 : myi1; \
;       _Pragma("unroll") for (int e = 0; e < 8; ++e) { const int idx_ = __builtin_amdgcn_readlane(isrc_, ((e0_) + e) & 63); \
;         BUF[e] = *(const u32x4*)((TAB) + (size_t)idx_ * 1024 + lane * 16); } } while (0)
; DEV void peer_gather(const Params& P, int l, int m0, const int* idxs, const float* gs) {
;     ...
; #pragma nounroll
;     for (int e0 = 0; e0 < 128; e0 += 16) {
;       PG_ISSUE(b1, V, e0 + 8);
;       if (e0 == 64 && i + 1 < 16) sort_lists(lane, ni0, ni1, ng0, ng1);
;       PG_V16(b0, e0);
;       if (e0 + 16 < 128) PG_ISSUE(b0, V, e0 + 16);
;       PG_V16(b1, e0 + 8);
;     }
;     ...
;     float ss = 0.f;
; #pragma unroll
;     for (int q = 0; q < 4; ++q) {
;       hv[q][0] += acc[2 * q][0] * TAB_INV; hv[q][1] += acc[2 * q][1] * TAB_INV; hv[q][2] += acc[2 * q + 1][0] * TAB_INV; hv[q][3] += acc[2 * q + 1][1] * TAB_INV;
;       ss += hv[q][0] * hv[q][0] + hv[q][1] * hv[q][1] + hv[q][2] * hv[q][2] + hv[q][3] * hv[q][3];
;       *(f32x4*)(hrow + 4 * q) = hv[q];
;     }
;     const float rstd = rsqrtf(wave_sum(ss) * (1.f / DM) + EPS);
;     u32x4 oa, ob;
; #pragma unroll
;     for (int q = 0; q < 4; ++q) {
;       const f32x4 g = *(const f32x4*)(gp + lane * 16 + 4 * q);
	v_cvt_pk_f32_fp8_e32 v[104:105], v48
	v_cvt_pk_f32_fp8_e32 v[108:109], v52
	v_cvt_pk_f32_fp8_sdwa v[106:107], v48 src0_sel:WORD_1
	v_cvt_pk_f32_fp8_sdwa v[110:111], v52 src0_sel:WORD_1
	v_pk_fma_f32 v[64:65], v[104:105], v[96:97], v[64:65] op_sel_hi:[1,0,1]
	v_pk_fma_f32 v[66:67], v[106:107], v[96:97], v[66:67] op_sel_hi:[1,0,1]
	v_pk_fma_f32 v[64:65], v[108:109], v[96:97], v[64:65] op_sel:[0,1,0] op_sel_hi:[1,1,1]
	v_pk_fma_f32 v[66:67], v[110:111], v[96:97], v[66:67] op_sel:[0,1,0] op_sel_hi:[1,1,1]
	v_cvt_pk_f32_fp8_e32 v[104:105], v49
	v_cvt_pk_f32_fp8_e32 v[108:109], v53
	v_cvt_pk_f32_fp8_sdwa v[106:107], v49 src0_sel:WORD_1
	v_cvt_pk_f32_fp8_sdwa v[110:111], v53 src0_sel:WORD_1
	v_pk_fma_f32 v[68:69], v[104:105], v[96:97], v[68:69] op_sel_hi:[1,0,1]
	v_pk_fma_f32 v[70:71], v[106:107], v[96:97], v[70:71] op_sel_hi:[1,0,1]
	v_pk_fma_f32 v[68:69], v[108:109], v[96:97], v[68:69] op_sel:[0,1,0] op_sel_hi:[1,1,1]
	v_pk_fma_f32 v[70:71], v[110:111], v[96:97], v[70:71] op_sel:[0,1,0] op_sel_hi:[1,1,1]
	v_cvt_pk_f32_fp8_e32 v[104:105], v50
	v_cvt_pk_f32_fp8_e32 v[108:109], v54
	v_cvt_pk_f32_fp8_sdwa v[106:107], v50 src0_sel:WORD_1
	v_cvt_pk_f32_fp8_sdwa v[110:111], v54 src0_sel:WORD_1
	v_pk_fma_f32 v[72:73], v[104:105], v[96:97], v[72:73] op_sel_hi:[1,0,1]
	v_pk_fma_f32 v[74:75], v[106:107], v[96:97], v[74:75] op_sel_hi:[1,0,1]
	v_pk_fma_f32 v[72:73], v[108:109], v[96:97], v[72:73] op_sel:[0,1,0] op_sel_hi:[1,1,1]
	v_pk_fma_f32 v[74:75], v[110:111], v[96:97], v[74:75] op_sel:[0,1,0] op_sel_hi:[1,1,1]
	v_cvt_pk_f32_fp8_e32 v[104:105], v51
	v_cvt_pk_f32_fp8_e32 v[108:109], v55
	v_cvt_pk_f32_fp8_sdwa v[106:107], v51 src0_sel:WORD_1
	v_cvt_pk_f32_fp8_sdwa v[110:111], v55 src0_sel:WORD_1
	v_pk_fma_f32 v[76:77], v[104:105], v[96:97], v[76:77] op_sel_hi:[1,0,1]
	v_pk_fma_f32 v[78:79], v[106:107], v[96:97], v[78:79] op_sel_hi:[1,0,1]
	v_and_or_b32 v242, v242, s2, v240
	v_and_or_b32 v243, v243, s2, v240
	global_load_dwordx4 v[48:51], v242, s[80:81]
	global_load_dwordx4 v[52:55], v243, s[80:81]
	v_pk_fma_f32 v[76:77], v[108:109], v[96:97], v[76:77] op_sel:[0,1,0] op_sel_hi:[1,1,1]
	v_pk_fma_f32 v[78:79], v[110:111], v[96:97], v[78:79] op_sel:[0,1,0] op_sel_hi:[1,1,1]
	s_waitcnt vmcnt(16)
	v_cvt_pk_f32_fp8_e32 v[104:105], v56
	v_cvt_pk_f32_fp8_e32 v[108:109], v60
	v_cvt_pk_f32_fp8_sdwa v[106:107], v56 src0_sel:WORD_1
	v_cvt_pk_f32_fp8_sdwa v[110:111], v60 src0_sel:WORD_1
	v_pk_fma_f32 v[64:65], v[104:105], v[98:99], v[64:65] op_sel_hi:[1,0,1]
	v_pk_fma_f32 v[66:67], v[106:107], v[98:99], v[66:67] op_sel_hi:[1,0,1]
	v_pk_fma_f32 v[64:65], v[108:109], v[98:99], v[64:65] op_sel:[0,1,0] op_sel_hi:[1,1,1]
	v_pk_fma_f32 v[66:67], v[110:111], v[98:99], v[66:67] op_sel:[0,1,0] op_sel_hi:[1,1,1]
	v_cvt_pk_f32_fp8_e32 v[104:105], v57
	v_cvt_pk_f32_fp8_e32 v[108:109], v61
	v_cvt_pk_f32_fp8_sdwa v[106:107], v57 src0_sel:WORD_1
	v_cvt_pk_f32_fp8_sdwa v[110:111], v61 src0_sel:WORD_1
	v_pk_fma_f32 v[68:69], v[104:105], v[98:99], v[68:69] op_sel_hi:[1,0,1]
	v_pk_fma_f32 v[70:71], v[106:107], v[98:99], v[70:71] op_sel_hi:[1,0,1]
	v_pk_fma_f32 v[68:69], v[108:109], v[98:99], v[68:69] op_sel:[0,1,0] op_sel_hi:[1,1,1]
	v_pk_fma_f32 v[70:71], v[110:111], v[98:99], v[70:71] op_sel:[0,1,0] op_sel_hi:[1,1,1]
	v_cvt_pk_f32_fp8_e32 v[104:105], v58
	v_cvt_pk_f32_fp8_e32 v[108:109], v62
	v_cvt_pk_f32_fp8_sdwa v[106:107], v58 src0_sel:WORD_1
	v_cvt_pk_f32_fp8_sdwa v[110:111], v62 src0_sel:WORD_1
	v_pk_fma_f32 v[72:73], v[104:105], v[98:99], v[72:73] op_sel_hi:[1,0,1]
	v_pk_fma_f32 v[74:75], v[106:107], v[98:99], v[74:75] op_sel_hi:[1,0,1]
	v_pk_fma_f32 v[72:73], v[108:109], v[98:99], v[72:73] op_sel:[0,1,0] op_sel_hi:[1,1,1]
	v_pk_fma_f32 v[74:75], v[110:111], v[98:99], v[74:75] op_sel:[0,1,0] op_sel_hi:[1,1,1]
	v_cvt_pk_f32_fp8_e32 v[104:105], v59
	v_cvt_pk_f32_fp8_e32 v[108:109], v63
	v_cvt_pk_f32_fp8_sdwa v[106:107], v59 src0_sel:WORD_1
	v_cvt_pk_f32_fp8_sdwa v[110:111], v63 src0_sel:WORD_1
	v_pk_fma_f32 v[76:77], v[104:105], v[98:99], v[76:77] op_sel_hi:[1,0,1]
	v_pk_fma_f32 v[78:79], v[106:107], v[98:99], v[78:79] op_sel_hi:[1,0,1]
	v_and_or_b32 v244, v244, s2, v240
	v_and_or_b32 v245, v245, s2, v240
	global_load_dwordx4 v[56:59], v244, s[80:81]
	global_load_dwordx4 v[60:63], v245, s[80:81]
	v_pk_fma_f32 v[76:77], v[108:109], v[98:99], v[76:77] op_sel:[0,1,0] op_sel_hi:[1,1,1]
	v_pk_fma_f32 v[78:79], v[110:111], v[98:99], v[78:79] op_sel:[0,1,0] op_sel_hi:[1,1,1]
	s_add_u32 s92, s100, 2
	s_and_b32 s92, s92, 15
	v_lshl_add_u32 v116, s92, 9, v246
	ds_read_b128 v[112:115], v116
	ds_read_b128 v[138:141], v116 offset:16
	ds_read_b128 v[250:253], v116 offset:32
	ds_read_b128 v[242:245], v116 offset:48
	s_add_u32 s92, s100, 1
	s_and_b32 s92, s92, 15
	v_lshl_add_u32 v117, s92, 9, v247
	ds_read_b128 v[84:87], v117
	ds_read_b128 v[88:91], v117 offset:16
	ds_read_b128 v[92:95], v117 offset:32
	ds_read_b128 v[96:99], v117 offset:48
	s_nop 1
	v_permlane32_swap_b32_e32 v64, v66
	v_permlane32_swap_b32_e32 v65, v67
	v_permlane32_swap_b32_e32 v68, v70
	v_permlane32_swap_b32_e32 v69, v71
	v_permlane32_swap_b32_e32 v72, v74
	v_permlane32_swap_b32_e32 v73, v75
	v_permlane32_swap_b32_e32 v76, v78
	v_permlane32_swap_b32_e32 v77, v79
	v_add_f32_e32 v64, v64, v66
	v_add_f32_e32 v65, v65, v67
	v_add_f32_e32 v68, v68, v70
	v_add_f32_e32 v69, v69, v71
	v_add_f32_e32 v72, v72, v74
	v_add_f32_e32 v73, v73, v75
	v_add_f32_e32 v76, v76, v78
	v_add_f32_e32 v77, v77, v79
	s_nop 1
	v_permlane16_swap_b32_e32 v64, v68
	v_permlane16_swap_b32_e32 v65, v69
	v_permlane16_swap_b32_e32 v72, v76
	v_permlane16_swap_b32_e32 v73, v77
	v_add_f32_e32 v64, v64, v68
	v_add_f32_e32 v65, v65, v69
	v_add_f32_e32 v72, v72, v76
	v_add_f32_e32 v73, v73, v77
	s_nop 0
	v_cndmask_b32_e64 v66, v64, v72, s[88:89]
	v_cndmask_b32_e64 v67, v72, v64, s[88:89]
	v_cndmask_b32_e64 v74, v65, v73, s[88:89]
	v_cndmask_b32_e64 v75, v73, v65, s[88:89]
	s_nop 1
	v_add_f32_dpp v64, v67, v66 row_ror:8 row_mask:0xf bank_mask:0xf
	v_add_f32_dpp v65, v75, v74 row_ror:8 row_mask:0xf bank_mask:0xf
	v_fmac_f32_e32 v82, 0x3c800000, v64
	v_fmac_f32_e32 v83, 0x3c800000, v65
	global_store_dwordx2 v152, v[82:83], s[82:83]
	s_add_u32 s100, s100, 1
	s_cmp_lt_u32 s100, 128
	s_cbranch_scc1 .Lpg0_vloop
	s_waitcnt vmcnt(0) lgkmcnt(0)
	v_readfirstlane_b32 s88, v130
	v_readfirstlane_b32 s89, v131
	s_nop 4
	v_lshlrev_b32_e32 v117, 6, v233
	global_load_dwordx4 v[16:19], v117, s[88:89] offset:0
	global_load_dwordx4 v[20:23], v117, s[88:89] offset:16
	global_load_dwordx4 v[24:27], v117, s[88:89] offset:32
	global_load_dwordx4 v[28:31], v117, s[88:89] offset:48
	s_mov_b32 s2, 0

.Lpg1_act:
	v_readlane_b32 s82, v232, 1
	v_readlane_b32 s83, v232, 2
	s_nop 4
	s_lshl_b32 s98, s2, 11
	s_add_u32 s98, s98, s101
	v_add_u32_e32 v116, s98, v234
	v_add_u32_e32 v117, 0x10000, v116
	ds_read_b32 v0, v116 offset:0
	ds_read_b32 v8, v117 offset:0
	ds_read_b32 v1, v116 offset:256
	ds_read_b32 v9, v117 offset:256
	ds_read_b32 v2, v116 offset:512
	ds_read_b32 v10, v117 offset:512
	ds_read_b32 v3, v116 offset:768
	ds_read_b32 v11, v117 offset:768
	ds_read_b32 v4, v116 offset:1024
	ds_read_b32 v12, v117 offset:1024
	ds_read_b32 v5, v116 offset:1280
	ds_read_b32 v13, v117 offset:1280
	ds_read_b32 v6, v116 offset:1536
	ds_read_b32 v14, v117 offset:1536
	ds_read_b32 v7, v116 offset:1792
	ds_read_b32 v15, v117 offset:1792
	s_waitcnt lgkmcnt(0)
	s_lshl_b32 s99, s2, 2
	s_add_u32 s99, s99, s33
	s_add_u32 s99, s99, 0
	s_lshl_b32 s99, s99, 9
	v_and_b32_e32 v0, 0x7f, v0
	v_lshl_add_u32 v0, v0, 2, s99
	global_load_dword v16, v0, s[82:83]
	v_and_b32_e32 v1, 0x7f, v1
	v_lshl_add_u32 v1, v1, 2, s99
	global_load_dword v17, v1, s[82:83]
	s_lshl_b32 s99, s2, 2
	s_add_u32 s99, s99, s33
	s_add_u32 s99, s99, 1
	s_lshl_b32 s99, s99, 9
	v_and_b32_e32 v2, 0x7f, v2
	v_lshl_add_u32 v2, v2, 2, s99
	global_load_dword v18, v2, s[82:83]
	v_and_b32_e32 v3, 0x7f, v3
	v_lshl_add_u32 v3, v3, 2, s99
	global_load_dword v19, v3, s[82:83]
	s_lshl_b32 s99, s2, 2
	s_add_u32 s99, s99, s33
	s_add_u32 s99, s99, 2
	s_lshl_b32 s99, s99, 9
	v_and_b32_e32 v4, 0x7f, v4
	v_lshl_add_u32 v4, v4, 2, s99
	global_load_dword v20, v4, s[82:83]
	v_and_b32_e32 v5, 0x7f, v5
	v_lshl_add_u32 v5, v5, 2, s99
	global_load_dword v21, v5, s[82:83]
	s_lshl_b32 s99, s2, 2
	s_add_u32 s99, s99, s33
	s_add_u32 s99, s99, 3
	s_lshl_b32 s99, s99, 9
	v_and_b32_e32 v6, 0x7f, v6
	v_lshl_add_u32 v6, v6, 2, s99
	global_load_dword v22, v6, s[82:83]
	v_and_b32_e32 v7, 0x7f, v7
	v_lshl_add_u32 v7, v7, 2, s99
	global_load_dword v23, v7, s[82:83]
	v_mul_f32_e32 v8, 0x3c800000, v8
	v_mul_f32_e32 v9, 0x3c800000, v9
	v_mul_f32_e32 v10, 0x3c800000, v10
	v_mul_f32_e32 v11, 0x3c800000, v11
	v_mul_f32_e32 v12, 0x3c800000, v12
	v_mul_f32_e32 v13, 0x3c800000, v13
	v_mul_f32_e32 v14, 0x3c800000, v14
	v_mul_f32_e32 v15, 0x3c800000, v15
	v_mul_f32_e32 v24, 0x3d372713, v8
	v_mul_f32_e32 v25, 0x3d372713, v9
	v_mul_f32_e32 v26, 0x3d372713, v10
	v_mul_f32_e32 v27, 0x3d372713, v11
	v_mul_f32_e32 v28, 0x3d372713, v12
	v_mul_f32_e32 v29, 0x3d372713, v13
	v_mul_f32_e32 v30, 0x3d372713, v14
	v_mul_f32_e32 v31, 0x3d372713, v15
	v_mul_f32_e32 v24, v8, v24
	v_mul_f32_e32 v25, v9, v25
	v_mul_f32_e32 v26, v10, v26
	v_mul_f32_e32 v27, v11, v27
	v_mul_f32_e32 v28, v12, v28
	v_mul_f32_e32 v29, v13, v29
	v_mul_f32_e32 v30, v14, v30
	v_mul_f32_e32 v31, v15, v31
	v_fma_f32 v24, v8, v24, v8
	v_fma_f32 v25, v9, v25, v9
	v_fma_f32 v26, v10, v26, v10
	v_fma_f32 v27, v11, v27, v11
	v_fma_f32 v28, v12, v28, v12
	v_fma_f32 v29, v13, v29, v13
	v_fma_f32 v30, v14, v30, v14
	v_fma_f32 v31, v15, v31, v15
	v_mul_f32_e32 v24, 0xbfcc422a, v24
	v_mul_f32_e32 v25, 0xbfcc422a, v25
	v_mul_f32_e32 v26, 0xbfcc422a, v26
	v_mul_f32_e32 v27, 0xbfcc422a, v27
	v_mul_f32_e32 v28, 0xbfcc422a, v28
	v_mul_f32_e32 v29, 0xbfcc422a, v29
	v_mul_f32_e32 v30, 0xbfcc422a, v30
	v_mul_f32_e32 v31, 0xbfcc422a, v31
	v_mul_f32_e32 v24, 0x3fb8aa3b, v24
	v_mul_f32_e32 v25, 0x3fb8aa3b, v25
	v_mul_f32_e32 v26, 0x3fb8aa3b, v26
	v_mul_f32_e32 v27, 0x3fb8aa3b, v27
	v_mul_f32_e32 v28, 0x3fb8aa3b, v28
	v_mul_f32_e32 v29, 0x3fb8aa3b, v29
	v_mul_f32_e32 v30, 0x3fb8aa3b, v30
	v_mul_f32_e32 v31, 0x3fb8aa3b, v31
	v_exp_f32_e32 v24, v24
	v_exp_f32_e32 v25, v25
	v_exp_f32_e32 v26, v26
	v_exp_f32_e32 v27, v27
	v_exp_f32_e32 v28, v28
	v_exp_f32_e32 v29, v29
	v_exp_f32_e32 v30, v30
	v_exp_f32_e32 v31, v31
	s_nop 0
	v_add_f32_e32 v24, 1.0, v24
	v_add_f32_e32 v25, 1.0, v25
	v_add_f32_e32 v26, 1.0, v26
	v_add_f32_e32 v27, 1.0, v27
	v_add_f32_e32 v28, 1.0, v28
	v_add_f32_e32 v29, 1.0, v29
	v_add_f32_e32 v30, 1.0, v30
	v_add_f32_e32 v31, 1.0, v31
	v_rcp_f32_e32 v24, v24
	v_rcp_f32_e32 v25, v25
	v_rcp_f32_e32 v26, v26
	v_rcp_f32_e32 v27, v27
	v_rcp_f32_e32 v28, v28
	v_rcp_f32_e32 v29, v29
	v_rcp_f32_e32 v30, v30
	v_rcp_f32_e32 v31, v31
	s_nop 0
	v_mul_f32_e32 v24, v8, v24
	v_mul_f32_e32 v25, v9, v25
	v_mul_f32_e32 v26, v10, v26
	v_mul_f32_e32 v27, v11, v27
	v_mul_f32_e32 v28, v12, v28
	v_mul_f32_e32 v29, v13, v29
	v_mul_f32_e32 v30, v14, v30
	v_mul_f32_e32 v31, v15, v31
	s_waitcnt vmcnt(0)
	v_mul_f32_e32 v24, v24, v16
	ds_write_b32 v117, v24 offset:0
	v_mul_f32_e32 v25, v25, v17
	ds_write_b32 v117, v25 offset:256
	v_mul_f32_e32 v26, v26, v18
	ds_write_b32 v117, v26 offset:512
	v_mul_f32_e32 v27, v27, v19
	ds_write_b32 v117, v27 offset:768
	v_mul_f32_e32 v28, v28, v20
	ds_write_b32 v117, v28 offset:1024
	v_mul_f32_e32 v29, v29, v21
	ds_write_b32 v117, v29 offset:1280
	v_mul_f32_e32 v30, v30, v22
	ds_write_b32 v117, v30 offset:1536
	v_mul_f32_e32 v31, v31, v23
	ds_write_b32 v117, v31 offset:1792
	s_add_u32 s2, s2, 1
	s_cmp_lt_u32 s2, 4
	s_cbranch_scc1 .Lpg1_act
; #define PG_ISSUE(BUF, TAB, e0_) do { const int isrc_ = ((e0_) < 64) ? myi0 : myi1; \
;       _Pragma("unroll") for (int e = 0; e < 8; ++e) { const int idx_ = __builtin_amdgcn_readlane(isrc_, ((e0_) + e) & 63); \
;         BUF[e] = *(const u32x4*)((TAB) + (size_t)idx_ * 1024 + lane * 16); } } while (0)
; DEV void peer_gather(const Params& P, int l, int m0, const int* idxs, const float* gs) {
;     ...
;     PG_ISSUE(b0, U, 0);
; #pragma nounroll
;     for (int e0 = 0; e0 < 128; e0 += 16) {
;       PG_ISSUE(b1, U, e0 + 8);
;       PG_U8(b0, 0, e0);
;       if (e0 + 16 < 128) PG_ISSUE(b0, U, e0 + 16); else PG_ISSUE(b0, V, 0);
;       PG_U8(b1, 0, e0 + 8);
;     }
;     float* hrow = P.out + tok * DM + lane * 16;
;     f32x4 hv[4];
; #pragma unroll
;     for (int q = 0; q < 4; ++q) hv[q] = *(const f32x4*)(hrow + 4 * q);
;     if (i + 1 < 16) {
;       const int tn = tt + 1;
;       nxa = *(const u32x4*)(hn + (size_t)(m0 + tn) * DM + lane * 16); nxb = *(const u32x4*)(hn + (size_t)(m0 + tn) * DM + lane * 16 + 8);
;       ni0 = idxs[tn * 128 + lane]; ni1 = idxs[tn * 128 + 64 + lane]; ng0 = gs[tn * 128 + lane]; ng1 = gs[tn * 128 + 64 + lane];
;     }
; #pragma nounroll
;     for (int e0 = 0; e0 < 128; e0 += 16) {
;       PG_ISSUE(b1, V, e0 + 8);
;       if (e0 == 64 && i + 1 < 16) sort_lists(lane, ni0, ni1, ng0, ng1);
;       PG_V16(b0, e0);
;       if (e0 + 16 < 128) PG_ISSUE(b0, V, e0 + 16);
;       PG_V16(b1, e0 + 8);
	s_waitcnt lgkmcnt(0)
	v_readfirstlane_b32 s80, v128
	v_readfirstlane_b32 s81, v129
	s_nop 4
	v_readfirstlane_b32 s82, v132
	v_readfirstlane_b32 s83, v133
	s_nop 4
	s_mov_b32 s2, 0xffffff80
	s_lshl_b32 vcc_lo, s3, 12
	s_add_u32 s82, s82, vcc_lo
	s_addc_u32 s83, s83, 0
	s_mov_b32 s88, 0xff00ff00
	s_mov_b32 s89, 0xff00ff00
	v_lshl_add_u32 v246, v237, 4, s101
	v_add_u32_e32 v247, 0x10000, v246
	v_lshlrev_b32_e32 v238, 2, v235
	v_bfe_u32 v116, v233, 5, 1
	v_lshl_add_u32 v238, v116, 3, v238
	v_bfe_u32 v116, v233, 4, 1
	v_lshl_add_u32 v238, v116, 4, v238
	v_bfe_u32 v116, v233, 3, 1
	v_lshl_add_u32 v238, v116, 5, v238
	s_mov_b32 s100, 0
	s_mov_b32 s98, 0
	s_mov_b32 s99, 0
	v_lshl_add_u32 v116, s98, 9, v246
	ds_read_b128 v[112:115], v116
	ds_read_b128 v[138:141], v116 offset:16
	ds_read_b128 v[250:253], v116 offset:32
	ds_read_b128 v[242:245], v116 offset:48
	v_lshl_or_b32 v240, s99, 21, v235
	s_waitcnt lgkmcnt(0)
	v_and_or_b32 v112, v112, s2, v240
	v_and_or_b32 v113, v113, s2, v240
	global_load_dwordx4 v[0:3], v112, s[80:81]
	global_load_dwordx4 v[4:7], v113, s[80:81]
	v_and_or_b32 v114, v114, s2, v240
	v_and_or_b32 v115, v115, s2, v240
	global_load_dwordx4 v[8:11], v114, s[80:81]
	global_load_dwordx4 v[12:15], v115, s[80:81]
	v_and_or_b32 v138, v138, s2, v240
	v_and_or_b32 v139, v139, s2, v240
	global_load_dwordx4 v[16:19], v138, s[80:81]
	global_load_dwordx4 v[20:23], v139, s[80:81]
	v_and_or_b32 v140, v140, s2, v240
	v_and_or_b32 v141, v141, s2, v240
	global_load_dwordx4 v[24:27], v140, s[80:81]
	global_load_dwordx4 v[28:31], v141, s[80:81]
	v_and_or_b32 v250, v250, s2, v240
	v_and_or_b32 v251, v251, s2, v240
	global_load_dwordx4 v[32:35], v250, s[80:81]
	global_load_dwordx4 v[36:39], v251, s[80:81]
	v_and_or_b32 v252, v252, s2, v240
	v_and_or_b32 v253, v253, s2, v240
	global_load_dwordx4 v[40:43], v252, s[80:81]
	global_load_dwordx4 v[44:47], v253, s[80:81]
	v_and_or_b32 v242, v242, s2, v240
	v_and_or_b32 v243, v243, s2, v240
	global_load_dwordx4 v[48:51], v242, s[80:81]
	global_load_dwordx4 v[52:55], v243, s[80:81]
	v_and_or_b32 v244, v244, s2, v240
	v_and_or_b32 v245, v245, s2, v240
	global_load_dwordx4 v[56:59], v244, s[80:81]
	global_load_dwordx4 v[60:63], v245, s[80:81]
	s_mov_b32 s92, 1
	v_lshl_add_u32 v116, s92, 9, v246
	ds_read_b128 v[112:115], v116
	ds_read_b128 v[138:141], v116 offset:16
	ds_read_b128 v[250:253], v116 offset:32
	ds_read_b128 v[242:245], v116 offset:48
	v_lshl_add_u32 v117, s98, 9, v247
	ds_read_b128 v[84:87], v117
	ds_read_b128 v[88:91], v117 offset:16
	ds_read_b128 v[92:95], v117 offset:32
	ds_read_b128 v[96:99], v117 offset:48
	s_mov_b32 s98, 0
	s_mov_b32 s99, 0
	s_lshl3_add_u32 vcc_lo, s98, s99
	v_lshl_add_u32 v119, vcc_lo, 9, v238
	global_load_dwordx2 v[80:81], v119, s[82:83]
	s_waitcnt vmcnt(0)
